# narrow K-loop for the low-rank column tile (skips unused weight rows/MFMAs) + priority raise for sample scans
# speedup vs baseline: 1.0947x; 1.0119x over previous
.LBB0_276:
	s_cmpk_gt_i32 s10, 0x7f
	s_cbranch_scc1 .Lprio_skip
	s_setprio 3

.LBB0_343:
	s_setprio 0
	v_readlane_b32 s0, v254, 32
	v_readlane_b32 s1, v254, 33
	s_and_b64 vcc, exec, s[0:1]
	s_cbranch_vccz .LBB0_345
	v_readlane_b32 s0, v254, 20
	v_readlane_b32 s1, v254, 21
	s_and_b64 s[0:1], exec, s[0:1]
	s_mov_b32 s0, 0x6000000
	s_cselect_b32 s0, s0, 0x6800000
	s_add_u32 s0, s86, s0
	s_addc_u32 s1, s87, 0
	v_readlane_b32 s2, v254, 22
	v_readlane_b32 s3, v254, 23
	s_add_u32 s0, s0, s2
	s_addc_u32 s1, s1, s3
	v_ashrrev_i32_e32 v111, 31, v110
	v_lshl_add_u64 v[4:5], v[110:111], 2, s[0:1]
	s_movk_i32 s0, 0x2000
	v_add_co_u32_e32 v6, vcc, s0, v4
	s_movk_i32 s0, 0x4000
	s_nop 0
	v_addc_co_u32_e32 v7, vcc, 0, v5, vcc
	global_store_dword v[4:5], v22, off
	global_store_dword v[4:5], v23, off offset:512
	global_store_dword v[4:5], v24, off offset:1024
	global_store_dword v[4:5], v25, off offset:1536
	global_store_dword v[4:5], v26, off offset:64
	global_store_dword v[4:5], v27, off offset:576
	global_store_dword v[4:5], v28, off offset:1088
	global_store_dword v[4:5], v29, off offset:1600
	global_store_dword v[6:7], v30, off
	global_store_dword v[6:7], v31, off offset:512
	global_store_dword v[6:7], v32, off offset:1024
	global_store_dword v[6:7], v33, off offset:1536
	global_store_dword v[6:7], v34, off offset:64
	global_store_dword v[6:7], v35, off offset:576
	global_store_dword v[6:7], v36, off offset:1088
	global_store_dword v[6:7], v37, off offset:1600
	v_add_co_u32_e32 v6, vcc, s0, v4
	s_movk_i32 s0, 0x6000
	s_nop 0
	v_addc_co_u32_e32 v7, vcc, 0, v5, vcc
	v_add_co_u32_e32 v4, vcc, s0, v4
	global_store_dword v[6:7], v38, off
	global_store_dword v[6:7], v39, off offset:512
	global_store_dword v[6:7], v40, off offset:1024
	global_store_dword v[6:7], v41, off offset:1536
	global_store_dword v[6:7], v42, off offset:64
	global_store_dword v[6:7], v43, off offset:576
	global_store_dword v[6:7], v44, off offset:1088
	global_store_dword v[6:7], v45, off offset:1600
	v_addc_co_u32_e32 v5, vcc, 0, v5, vcc
	global_store_dword v[4:5], v46, off
	global_store_dword v[4:5], v47, off offset:512
	global_store_dword v[4:5], v48, off offset:1024
	global_store_dword v[4:5], v49, off offset:1536
	global_store_dword v[4:5], v50, off offset:64
	global_store_dword v[4:5], v51, off offset:576
	global_store_dword v[4:5], v52, off offset:1088
	global_store_dword v[4:5], v53, off offset:1600

.LBB0_346:
	v_and_b32_e32 v76, 63, v0
	v_lshrrev_b32_e32 v77, 6, v0
	v_and_b32_e32 v93, 15, v0
	v_readfirstlane_b32 s9, v77
	v_lshrrev_b32_e32 v78, 3, v76
	v_and_b32_e32 v79, 7, v76
	v_lshrrev_b32_e32 v80, 1, v78
	s_and_b32 s4, s9, 1
	s_lshl_b32 s4, s4, 2
	v_or_b32_e32 v80, s4, v80
	v_xor_b32_e32 v79, v79, v80
	s_lshl_b32 s4, s9, 3
	v_add_u32_e32 v78, s4, v78
	v_lshlrev_b32_e32 v78, 11, v78
	v_lshl_add_u32 v56, v79, 4, v78
	v_add_u32_e32 v57, 0x10000, v56
	v_add_u32_e32 v58, 0x20000, v56
	v_add_u32_e32 v59, 0x30000, v56
	s_lshl_b32 s4, s22, 18
	s_add_u32 s0, s48, s4
	s_addc_u32 s1, s49, 0
	s_lshl_b32 s4, s64, 18
	s_add_u32 s2, s44, s4
	s_addc_u32 s3, s45, 0
	s_lshl_b32 s4, s9, 10
	s_add_u32 s4, s4, 16
	v_bfe_u32 v2, v0, 4, 2
	v_bfe_u32 v81, v0, 1, 3
	v_xor_b32_e32 v82, v2, v81
	v_or_b32_e32 v83, 4, v2
	v_xor_b32_e32 v83, v83, v81
	v_lshlrev_b32_e32 v82, 4, v82
	v_lshlrev_b32_e32 v83, 4, v83
	v_lshlrev_b32_e32 v84, 7, v93
	v_ashrrev_i32_e32 v92, 7, v0
	s_lshr_b32 s9, s9, 1
	s_lshl_b32 s9, s9, 13
	v_add3_u32 v64, v84, s9, 16
	v_add_u32_e32 v65, v64, v83
	v_add_u32_e32 v64, v64, v82
	v_bfe_u32 v85, v0, 6, 1
	s_lshl_b32 s9, s64, 7
	v_lshl_or_b32 v94, v85, 6, s9
	v_lshlrev_b32_e32 v85, 13, v85
	v_add3_u32 v66, v84, v85, 16
	v_add_u32_e32 v66, 0x4000, v66
	v_add_u32_e32 v67, v66, v83
	v_add_u32_e32 v66, v66, v82
	v_mov_b32_e32 v60, 0
	v_mov_b32_e32 v61, 0
	v_mov_b32_e32 v62, 0
	v_mov_b32_e32 v63, 0
	v_mov_b32_e32 v68, 0
	v_mov_b32_e32 v69, 0
	v_mov_b32_e32 v70, 0
	v_mov_b32_e32 v71, 0
	v_mov_b32_e32 v52, 0
	v_mov_b32_e32 v53, 0
	v_mov_b32_e32 v54, 0
	v_mov_b32_e32 v55, 0
	v_mov_b32_e32 v40, 0
	v_mov_b32_e32 v41, 0
	v_mov_b32_e32 v42, 0
	v_mov_b32_e32 v43, 0
	v_mov_b32_e32 v72, 0
	v_mov_b32_e32 v73, 0
	v_mov_b32_e32 v74, 0
	v_mov_b32_e32 v75, 0
	v_mov_b32_e32 v48, 0
	v_mov_b32_e32 v49, 0
	v_mov_b32_e32 v50, 0
	v_mov_b32_e32 v51, 0
	v_mov_b32_e32 v44, 0
	v_mov_b32_e32 v45, 0
	v_mov_b32_e32 v46, 0
	v_mov_b32_e32 v47, 0
	v_mov_b32_e32 v36, 0
	v_mov_b32_e32 v37, 0
	v_mov_b32_e32 v38, 0
	v_mov_b32_e32 v39, 0
	v_mov_b32_e32 v32, 0
	v_mov_b32_e32 v33, 0
	v_mov_b32_e32 v34, 0
	v_mov_b32_e32 v35, 0
	v_mov_b32_e32 v28, 0
	v_mov_b32_e32 v29, 0
	v_mov_b32_e32 v30, 0
	v_mov_b32_e32 v31, 0
	v_mov_b32_e32 v24, 0
	v_mov_b32_e32 v25, 0
	v_mov_b32_e32 v26, 0
	v_mov_b32_e32 v27, 0
	v_mov_b32_e32 v20, 0
	v_mov_b32_e32 v21, 0
	v_mov_b32_e32 v22, 0
	v_mov_b32_e32 v23, 0
	v_mov_b32_e32 v16, 0
	v_mov_b32_e32 v17, 0
	v_mov_b32_e32 v18, 0
	v_mov_b32_e32 v19, 0
	v_mov_b32_e32 v12, 0
	v_mov_b32_e32 v13, 0
	v_mov_b32_e32 v14, 0
	v_mov_b32_e32 v15, 0
	v_mov_b32_e32 v8, 0
	v_mov_b32_e32 v9, 0
	v_mov_b32_e32 v10, 0
	v_mov_b32_e32 v11, 0
	v_mov_b32_e32 v4, 0
	v_mov_b32_e32 v5, 0
	v_mov_b32_e32 v6, 0
	v_mov_b32_e32 v7, 0
	s_cmp_eq_u32 s64, 24
	s_cbranch_scc1 .Lg1_narrow
	s_add_u32 m0, s4, 0x0
	s_nop 0
	global_load_lds_dwordx4 v56, s[0:1]
	s_add_u32 m0, s4, 0x1000
	s_nop 0
	global_load_lds_dwordx4 v57, s[0:1]
	s_add_u32 m0, s4, 0x2000
	s_nop 0
	global_load_lds_dwordx4 v58, s[0:1]
	s_add_u32 m0, s4, 0x3000
	s_nop 0
	global_load_lds_dwordx4 v59, s[0:1]
	s_add_u32 m0, s4, 0x4000
	s_nop 0
	global_load_lds_dwordx4 v56, s[2:3]
	s_add_u32 m0, s4, 0x5000
	s_nop 0
	global_load_lds_dwordx4 v57, s[2:3]
	s_add_u32 m0, s4, 0x6000
	s_nop 0
	global_load_lds_dwordx4 v58, s[2:3]
	s_add_u32 m0, s4, 0x7000
	s_nop 0
	global_load_lds_dwordx4 v59, s[2:3]
	s_add_u32 s0, s0, 0x80
	s_addc_u32 s1, s1, 0
	s_add_u32 s2, s2, 0x80
	s_addc_u32 s3, s3, 0
	s_waitcnt vmcnt(0)
	s_barrier
	ds_read_b128 v[140:143], v66 offset:0
	ds_read_b128 v[144:147], v66 offset:2048
	ds_read_b128 v[148:151], v66 offset:4096
	ds_read_b128 v[152:155], v66 offset:6144
	ds_read_b128 v[156:159], v64 offset:0
	ds_read_b128 v[160:163], v64 offset:2048
	ds_read_b128 v[164:167], v64 offset:4096
	ds_read_b128 v[168:171], v64 offset:6144
	s_waitcnt lgkmcnt(0)
	ds_read_b128 v[172:175], v67 offset:0
	ds_read_b128 v[176:179], v67 offset:2048
	ds_read_b128 v[180:183], v67 offset:4096
	ds_read_b128 v[184:187], v67 offset:6144
	ds_read_b128 v[188:191], v65 offset:0
	ds_read_b128 v[192:195], v65 offset:2048
	ds_read_b128 v[196:199], v65 offset:4096
	ds_read_b128 v[200:203], v65 offset:6144
	v_mfma_f32_16x16x32_bf16 v[60:63], v[140:143], v[156:159], v[60:63]
	v_mfma_f32_16x16x32_bf16 v[68:71], v[140:143], v[160:163], v[68:71]
	s_add_u32 m0, s4, 0x8000
	s_nop 0
	global_load_lds_dwordx4 v56, s[0:1]
	v_mfma_f32_16x16x32_bf16 v[52:55], v[140:143], v[164:167], v[52:55]
	v_mfma_f32_16x16x32_bf16 v[40:43], v[140:143], v[168:171], v[40:43]
	s_add_u32 m0, s4, 0x9000
	s_nop 0
	global_load_lds_dwordx4 v57, s[0:1]
	v_mfma_f32_16x16x32_bf16 v[72:75], v[144:147], v[156:159], v[72:75]
	v_mfma_f32_16x16x32_bf16 v[48:51], v[144:147], v[160:163], v[48:51]
	s_add_u32 m0, s4, 0xa000
	s_nop 0
	global_load_lds_dwordx4 v58, s[0:1]
	v_mfma_f32_16x16x32_bf16 v[44:47], v[144:147], v[164:167], v[44:47]
	v_mfma_f32_16x16x32_bf16 v[36:39], v[144:147], v[168:171], v[36:39]
	s_add_u32 m0, s4, 0xb000
	s_nop 0
	global_load_lds_dwordx4 v59, s[0:1]
	v_mfma_f32_16x16x32_bf16 v[32:35], v[148:151], v[156:159], v[32:35]
	v_mfma_f32_16x16x32_bf16 v[28:31], v[148:151], v[160:163], v[28:31]
	s_add_u32 m0, s4, 0xc000
	s_nop 0
	global_load_lds_dwordx4 v56, s[2:3]
	v_mfma_f32_16x16x32_bf16 v[24:27], v[148:151], v[164:167], v[24:27]
	v_mfma_f32_16x16x32_bf16 v[20:23], v[148:151], v[168:171], v[20:23]
	s_add_u32 m0, s4, 0xd000
	s_nop 0
	global_load_lds_dwordx4 v57, s[2:3]
	v_mfma_f32_16x16x32_bf16 v[16:19], v[152:155], v[156:159], v[16:19]
	v_mfma_f32_16x16x32_bf16 v[12:15], v[152:155], v[160:163], v[12:15]
	s_add_u32 m0, s4, 0xe000
	s_nop 0
	global_load_lds_dwordx4 v58, s[2:3]
	v_mfma_f32_16x16x32_bf16 v[8:11], v[152:155], v[164:167], v[8:11]
	v_mfma_f32_16x16x32_bf16 v[4:7], v[152:155], v[168:171], v[4:7]
	s_add_u32 m0, s4, 0xf000
	s_nop 0
	global_load_lds_dwordx4 v59, s[2:3]
	s_add_u32 s0, s0, 0x80
	s_addc_u32 s1, s1, 0
	s_add_u32 s2, s2, 0x80
	s_addc_u32 s3, s3, 0
	s_waitcnt vmcnt(0) lgkmcnt(0)
	s_barrier
	ds_read_b128 v[140:143], v66 offset:32768
	ds_read_b128 v[144:147], v66 offset:34816
	ds_read_b128 v[148:151], v66 offset:36864
	ds_read_b128 v[152:155], v66 offset:38912
	ds_read_b128 v[156:159], v64 offset:32768
	ds_read_b128 v[160:163], v64 offset:34816
	ds_read_b128 v[164:167], v64 offset:36864
	ds_read_b128 v[168:171], v64 offset:38912
	v_mfma_f32_16x16x32_bf16 v[60:63], v[172:175], v[188:191], v[60:63]
	v_mfma_f32_16x16x32_bf16 v[68:71], v[172:175], v[192:195], v[68:71]
	v_mfma_f32_16x16x32_bf16 v[52:55], v[172:175], v[196:199], v[52:55]
	v_mfma_f32_16x16x32_bf16 v[40:43], v[172:175], v[200:203], v[40:43]
	v_mfma_f32_16x16x32_bf16 v[72:75], v[176:179], v[188:191], v[72:75]
	v_mfma_f32_16x16x32_bf16 v[48:51], v[176:179], v[192:195], v[48:51]
	v_mfma_f32_16x16x32_bf16 v[44:47], v[176:179], v[196:199], v[44:47]
	v_mfma_f32_16x16x32_bf16 v[36:39], v[176:179], v[200:203], v[36:39]
	v_mfma_f32_16x16x32_bf16 v[32:35], v[180:183], v[188:191], v[32:35]
	v_mfma_f32_16x16x32_bf16 v[28:31], v[180:183], v[192:195], v[28:31]
	v_mfma_f32_16x16x32_bf16 v[24:27], v[180:183], v[196:199], v[24:27]
	v_mfma_f32_16x16x32_bf16 v[20:23], v[180:183], v[200:203], v[20:23]
	v_mfma_f32_16x16x32_bf16 v[16:19], v[184:187], v[188:191], v[16:19]
	v_mfma_f32_16x16x32_bf16 v[12:15], v[184:187], v[192:195], v[12:15]
	v_mfma_f32_16x16x32_bf16 v[8:11], v[184:187], v[196:199], v[8:11]
	v_mfma_f32_16x16x32_bf16 v[4:7], v[184:187], v[200:203], v[4:7]
	s_waitcnt lgkmcnt(0)
	ds_read_b128 v[172:175], v67 offset:32768
	ds_read_b128 v[176:179], v67 offset:34816
	ds_read_b128 v[180:183], v67 offset:36864
	ds_read_b128 v[184:187], v67 offset:38912
	ds_read_b128 v[188:191], v65 offset:32768
	ds_read_b128 v[192:195], v65 offset:34816
	ds_read_b128 v[196:199], v65 offset:36864
	ds_read_b128 v[200:203], v65 offset:38912
	v_mfma_f32_16x16x32_bf16 v[60:63], v[140:143], v[156:159], v[60:63]
	v_mfma_f32_16x16x32_bf16 v[68:71], v[140:143], v[160:163], v[68:71]
	s_add_u32 m0, s4, 0x0
	s_nop 0
	global_load_lds_dwordx4 v56, s[0:1]
	v_mfma_f32_16x16x32_bf16 v[52:55], v[140:143], v[164:167], v[52:55]
	v_mfma_f32_16x16x32_bf16 v[40:43], v[140:143], v[168:171], v[40:43]
	s_add_u32 m0, s4, 0x1000
	s_nop 0
	global_load_lds_dwordx4 v57, s[0:1]
	v_mfma_f32_16x16x32_bf16 v[72:75], v[144:147], v[156:159], v[72:75]
	v_mfma_f32_16x16x32_bf16 v[48:51], v[144:147], v[160:163], v[48:51]
	s_add_u32 m0, s4, 0x2000
	s_nop 0
	global_load_lds_dwordx4 v58, s[0:1]
	v_mfma_f32_16x16x32_bf16 v[44:47], v[144:147], v[164:167], v[44:47]
	v_mfma_f32_16x16x32_bf16 v[36:39], v[144:147], v[168:171], v[36:39]
	s_add_u32 m0, s4, 0x3000
	s_nop 0
	global_load_lds_dwordx4 v59, s[0:1]
	v_mfma_f32_16x16x32_bf16 v[32:35], v[148:151], v[156:159], v[32:35]
	v_mfma_f32_16x16x32_bf16 v[28:31], v[148:151], v[160:163], v[28:31]
	s_add_u32 m0, s4, 0x4000
	s_nop 0
	global_load_lds_dwordx4 v56, s[2:3]
	v_mfma_f32_16x16x32_bf16 v[24:27], v[148:151], v[164:167], v[24:27]
	v_mfma_f32_16x16x32_bf16 v[20:23], v[148:151], v[168:171], v[20:23]
	s_add_u32 m0, s4, 0x5000
	s_nop 0
	global_load_lds_dwordx4 v57, s[2:3]
	v_mfma_f32_16x16x32_bf16 v[16:19], v[152:155], v[156:159], v[16:19]
	v_mfma_f32_16x16x32_bf16 v[12:15], v[152:155], v[160:163], v[12:15]
	s_add_u32 m0, s4, 0x6000
	s_nop 0
	global_load_lds_dwordx4 v58, s[2:3]
	v_mfma_f32_16x16x32_bf16 v[8:11], v[152:155], v[164:167], v[8:11]
	v_mfma_f32_16x16x32_bf16 v[4:7], v[152:155], v[168:171], v[4:7]
	s_add_u32 m0, s4, 0x7000
	s_nop 0
	global_load_lds_dwordx4 v59, s[2:3]
	s_add_u32 s0, s0, 0x80
	s_addc_u32 s1, s1, 0
	s_add_u32 s2, s2, 0x80
	s_addc_u32 s3, s3, 0
	s_waitcnt vmcnt(0) lgkmcnt(0)
	s_barrier
	ds_read_b128 v[140:143], v66 offset:0
	ds_read_b128 v[144:147], v66 offset:2048
	ds_read_b128 v[148:151], v66 offset:4096
	ds_read_b128 v[152:155], v66 offset:6144
	ds_read_b128 v[156:159], v64 offset:0
	ds_read_b128 v[160:163], v64 offset:2048
	ds_read_b128 v[164:167], v64 offset:4096
	ds_read_b128 v[168:171], v64 offset:6144
	v_mfma_f32_16x16x32_bf16 v[60:63], v[172:175], v[188:191], v[60:63]
	v_mfma_f32_16x16x32_bf16 v[68:71], v[172:175], v[192:195], v[68:71]
	v_mfma_f32_16x16x32_bf16 v[52:55], v[172:175], v[196:199], v[52:55]
	v_mfma_f32_16x16x32_bf16 v[40:43], v[172:175], v[200:203], v[40:43]
	v_mfma_f32_16x16x32_bf16 v[72:75], v[176:179], v[188:191], v[72:75]
	v_mfma_f32_16x16x32_bf16 v[48:51], v[176:179], v[192:195], v[48:51]
	v_mfma_f32_16x16x32_bf16 v[44:47], v[176:179], v[196:199], v[44:47]
	v_mfma_f32_16x16x32_bf16 v[36:39], v[176:179], v[200:203], v[36:39]
	v_mfma_f32_16x16x32_bf16 v[32:35], v[180:183], v[188:191], v[32:35]
	v_mfma_f32_16x16x32_bf16 v[28:31], v[180:183], v[192:195], v[28:31]
	v_mfma_f32_16x16x32_bf16 v[24:27], v[180:183], v[196:199], v[24:27]
	v_mfma_f32_16x16x32_bf16 v[20:23], v[180:183], v[200:203], v[20:23]
	v_mfma_f32_16x16x32_bf16 v[16:19], v[184:187], v[188:191], v[16:19]
	v_mfma_f32_16x16x32_bf16 v[12:15], v[184:187], v[192:195], v[12:15]
	v_mfma_f32_16x16x32_bf16 v[8:11], v[184:187], v[196:199], v[8:11]
	v_mfma_f32_16x16x32_bf16 v[4:7], v[184:187], v[200:203], v[4:7]
	s_waitcnt lgkmcnt(0)
	ds_read_b128 v[172:175], v67 offset:0
	ds_read_b128 v[176:179], v67 offset:2048
	ds_read_b128 v[180:183], v67 offset:4096
	ds_read_b128 v[184:187], v67 offset:6144
	ds_read_b128 v[188:191], v65 offset:0
	ds_read_b128 v[192:195], v65 offset:2048
	ds_read_b128 v[196:199], v65 offset:4096
	ds_read_b128 v[200:203], v65 offset:6144
	v_mfma_f32_16x16x32_bf16 v[60:63], v[140:143], v[156:159], v[60:63]
	v_mfma_f32_16x16x32_bf16 v[68:71], v[140:143], v[160:163], v[68:71]
	s_add_u32 m0, s4, 0x8000
	s_nop 0
	global_load_lds_dwordx4 v56, s[0:1]
	v_mfma_f32_16x16x32_bf16 v[52:55], v[140:143], v[164:167], v[52:55]
	v_mfma_f32_16x16x32_bf16 v[40:43], v[140:143], v[168:171], v[40:43]
	s_add_u32 m0, s4, 0x9000
	s_nop 0
	global_load_lds_dwordx4 v57, s[0:1]
	v_mfma_f32_16x16x32_bf16 v[72:75], v[144:147], v[156:159], v[72:75]
	v_mfma_f32_16x16x32_bf16 v[48:51], v[144:147], v[160:163], v[48:51]
	s_add_u32 m0, s4, 0xa000
	s_nop 0
	global_load_lds_dwordx4 v58, s[0:1]
	v_mfma_f32_16x16x32_bf16 v[44:47], v[144:147], v[164:167], v[44:47]
	v_mfma_f32_16x16x32_bf16 v[36:39], v[144:147], v[168:171], v[36:39]
	s_add_u32 m0, s4, 0xb000
	s_nop 0
	global_load_lds_dwordx4 v59, s[0:1]
	v_mfma_f32_16x16x32_bf16 v[32:35], v[148:151], v[156:159], v[32:35]
	v_mfma_f32_16x16x32_bf16 v[28:31], v[148:151], v[160:163], v[28:31]
	s_add_u32 m0, s4, 0xc000
	s_nop 0
	global_load_lds_dwordx4 v56, s[2:3]
	v_mfma_f32_16x16x32_bf16 v[24:27], v[148:151], v[164:167], v[24:27]
	v_mfma_f32_16x16x32_bf16 v[20:23], v[148:151], v[168:171], v[20:23]
	s_add_u32 m0, s4, 0xd000
	s_nop 0
	global_load_lds_dwordx4 v57, s[2:3]
	v_mfma_f32_16x16x32_bf16 v[16:19], v[152:155], v[156:159], v[16:19]
	v_mfma_f32_16x16x32_bf16 v[12:15], v[152:155], v[160:163], v[12:15]
	s_add_u32 m0, s4, 0xe000
	s_nop 0
	global_load_lds_dwordx4 v58, s[2:3]
	v_mfma_f32_16x16x32_bf16 v[8:11], v[152:155], v[164:167], v[8:11]
	v_mfma_f32_16x16x32_bf16 v[4:7], v[152:155], v[168:171], v[4:7]
	s_add_u32 m0, s4, 0xf000
	s_nop 0
	global_load_lds_dwordx4 v59, s[2:3]
	s_add_u32 s0, s0, 0x80
	s_addc_u32 s1, s1, 0
	s_add_u32 s2, s2, 0x80
	s_addc_u32 s3, s3, 0
	s_waitcnt vmcnt(0) lgkmcnt(0)
	s_barrier
	ds_read_b128 v[140:143], v66 offset:32768
	ds_read_b128 v[144:147], v66 offset:34816
	ds_read_b128 v[148:151], v66 offset:36864
	ds_read_b128 v[152:155], v66 offset:38912
	ds_read_b128 v[156:159], v64 offset:32768
	ds_read_b128 v[160:163], v64 offset:34816
	ds_read_b128 v[164:167], v64 offset:36864
	ds_read_b128 v[168:171], v64 offset:38912
	v_mfma_f32_16x16x32_bf16 v[60:63], v[172:175], v[188:191], v[60:63]
	v_mfma_f32_16x16x32_bf16 v[68:71], v[172:175], v[192:195], v[68:71]
	v_mfma_f32_16x16x32_bf16 v[52:55], v[172:175], v[196:199], v[52:55]
	v_mfma_f32_16x16x32_bf16 v[40:43], v[172:175], v[200:203], v[40:43]
	v_mfma_f32_16x16x32_bf16 v[72:75], v[176:179], v[188:191], v[72:75]
	v_mfma_f32_16x16x32_bf16 v[48:51], v[176:179], v[192:195], v[48:51]
	v_mfma_f32_16x16x32_bf16 v[44:47], v[176:179], v[196:199], v[44:47]
	v_mfma_f32_16x16x32_bf16 v[36:39], v[176:179], v[200:203], v[36:39]
	v_mfma_f32_16x16x32_bf16 v[32:35], v[180:183], v[188:191], v[32:35]
	v_mfma_f32_16x16x32_bf16 v[28:31], v[180:183], v[192:195], v[28:31]
	v_mfma_f32_16x16x32_bf16 v[24:27], v[180:183], v[196:199], v[24:27]
	v_mfma_f32_16x16x32_bf16 v[20:23], v[180:183], v[200:203], v[20:23]
	v_mfma_f32_16x16x32_bf16 v[16:19], v[184:187], v[188:191], v[16:19]
	v_mfma_f32_16x16x32_bf16 v[12:15], v[184:187], v[192:195], v[12:15]
	v_mfma_f32_16x16x32_bf16 v[8:11], v[184:187], v[196:199], v[8:11]
	v_mfma_f32_16x16x32_bf16 v[4:7], v[184:187], v[200:203], v[4:7]
	s_waitcnt lgkmcnt(0)
	ds_read_b128 v[172:175], v67 offset:32768
	ds_read_b128 v[176:179], v67 offset:34816
	ds_read_b128 v[180:183], v67 offset:36864
	ds_read_b128 v[184:187], v67 offset:38912
	ds_read_b128 v[188:191], v65 offset:32768
	ds_read_b128 v[192:195], v65 offset:34816
	ds_read_b128 v[196:199], v65 offset:36864
	ds_read_b128 v[200:203], v65 offset:38912
	v_mfma_f32_16x16x32_bf16 v[60:63], v[140:143], v[156:159], v[60:63]
	v_mfma_f32_16x16x32_bf16 v[68:71], v[140:143], v[160:163], v[68:71]
	s_add_u32 m0, s4, 0x0
	s_nop 0
	global_load_lds_dwordx4 v56, s[0:1]
	v_mfma_f32_16x16x32_bf16 v[52:55], v[140:143], v[164:167], v[52:55]
	v_mfma_f32_16x16x32_bf16 v[40:43], v[140:143], v[168:171], v[40:43]
	s_add_u32 m0, s4, 0x1000
	s_nop 0
	global_load_lds_dwordx4 v57, s[0:1]
	v_mfma_f32_16x16x32_bf16 v[72:75], v[144:147], v[156:159], v[72:75]
	v_mfma_f32_16x16x32_bf16 v[48:51], v[144:147], v[160:163], v[48:51]
	s_add_u32 m0, s4, 0x2000
	s_nop 0
	global_load_lds_dwordx4 v58, s[0:1]
	v_mfma_f32_16x16x32_bf16 v[44:47], v[144:147], v[164:167], v[44:47]
	v_mfma_f32_16x16x32_bf16 v[36:39], v[144:147], v[168:171], v[36:39]
	s_add_u32 m0, s4, 0x3000
	s_nop 0
	global_load_lds_dwordx4 v59, s[0:1]
	v_mfma_f32_16x16x32_bf16 v[32:35], v[148:151], v[156:159], v[32:35]
	v_mfma_f32_16x16x32_bf16 v[28:31], v[148:151], v[160:163], v[28:31]
	s_add_u32 m0, s4, 0x4000
	s_nop 0
	global_load_lds_dwordx4 v56, s[2:3]
	v_mfma_f32_16x16x32_bf16 v[24:27], v[148:151], v[164:167], v[24:27]
	v_mfma_f32_16x16x32_bf16 v[20:23], v[148:151], v[168:171], v[20:23]
	s_add_u32 m0, s4, 0x5000
	s_nop 0
	global_load_lds_dwordx4 v57, s[2:3]
	v_mfma_f32_16x16x32_bf16 v[16:19], v[152:155], v[156:159], v[16:19]
	v_mfma_f32_16x16x32_bf16 v[12:15], v[152:155], v[160:163], v[12:15]
	s_add_u32 m0, s4, 0x6000
	s_nop 0
	global_load_lds_dwordx4 v58, s[2:3]
	v_mfma_f32_16x16x32_bf16 v[8:11], v[152:155], v[164:167], v[8:11]
	v_mfma_f32_16x16x32_bf16 v[4:7], v[152:155], v[168:171], v[4:7]
	s_add_u32 m0, s4, 0x7000
	s_nop 0
	global_load_lds_dwordx4 v59, s[2:3]
	s_add_u32 s0, s0, 0x80
	s_addc_u32 s1, s1, 0
	s_add_u32 s2, s2, 0x80
	s_addc_u32 s3, s3, 0
	s_waitcnt vmcnt(0) lgkmcnt(0)
	s_barrier
	ds_read_b128 v[140:143], v66 offset:0
	ds_read_b128 v[144:147], v66 offset:2048
	ds_read_b128 v[148:151], v66 offset:4096
	ds_read_b128 v[152:155], v66 offset:6144
	ds_read_b128 v[156:159], v64 offset:0
	ds_read_b128 v[160:163], v64 offset:2048
	ds_read_b128 v[164:167], v64 offset:4096
	ds_read_b128 v[168:171], v64 offset:6144
	v_mfma_f32_16x16x32_bf16 v[60:63], v[172:175], v[188:191], v[60:63]
	v_mfma_f32_16x16x32_bf16 v[68:71], v[172:175], v[192:195], v[68:71]
	v_mfma_f32_16x16x32_bf16 v[52:55], v[172:175], v[196:199], v[52:55]
	v_mfma_f32_16x16x32_bf16 v[40:43], v[172:175], v[200:203], v[40:43]
	v_mfma_f32_16x16x32_bf16 v[72:75], v[176:179], v[188:191], v[72:75]
	v_mfma_f32_16x16x32_bf16 v[48:51], v[176:179], v[192:195], v[48:51]
	v_mfma_f32_16x16x32_bf16 v[44:47], v[176:179], v[196:199], v[44:47]
	v_mfma_f32_16x16x32_bf16 v[36:39], v[176:179], v[200:203], v[36:39]
	v_mfma_f32_16x16x32_bf16 v[32:35], v[180:183], v[188:191], v[32:35]
	v_mfma_f32_16x16x32_bf16 v[28:31], v[180:183], v[192:195], v[28:31]
	v_mfma_f32_16x16x32_bf16 v[24:27], v[180:183], v[196:199], v[24:27]
	v_mfma_f32_16x16x32_bf16 v[20:23], v[180:183], v[200:203], v[20:23]
	v_mfma_f32_16x16x32_bf16 v[16:19], v[184:187], v[188:191], v[16:19]
	v_mfma_f32_16x16x32_bf16 v[12:15], v[184:187], v[192:195], v[12:15]
	v_mfma_f32_16x16x32_bf16 v[8:11], v[184:187], v[196:199], v[8:11]
	v_mfma_f32_16x16x32_bf16 v[4:7], v[184:187], v[200:203], v[4:7]
	s_waitcnt lgkmcnt(0)
	ds_read_b128 v[172:175], v67 offset:0
	ds_read_b128 v[176:179], v67 offset:2048
	ds_read_b128 v[180:183], v67 offset:4096
	ds_read_b128 v[184:187], v67 offset:6144
	ds_read_b128 v[188:191], v65 offset:0
	ds_read_b128 v[192:195], v65 offset:2048
	ds_read_b128 v[196:199], v65 offset:4096
	ds_read_b128 v[200:203], v65 offset:6144
	v_mfma_f32_16x16x32_bf16 v[60:63], v[140:143], v[156:159], v[60:63]
	v_mfma_f32_16x16x32_bf16 v[68:71], v[140:143], v[160:163], v[68:71]
	s_add_u32 m0, s4, 0x8000
	s_nop 0
	global_load_lds_dwordx4 v56, s[0:1]
	v_mfma_f32_16x16x32_bf16 v[52:55], v[140:143], v[164:167], v[52:55]
	v_mfma_f32_16x16x32_bf16 v[40:43], v[140:143], v[168:171], v[40:43]
	s_add_u32 m0, s4, 0x9000
	s_nop 0
	global_load_lds_dwordx4 v57, s[0:1]
	v_mfma_f32_16x16x32_bf16 v[72:75], v[144:147], v[156:159], v[72:75]
	v_mfma_f32_16x16x32_bf16 v[48:51], v[144:147], v[160:163], v[48:51]
	s_add_u32 m0, s4, 0xa000
	s_nop 0
	global_load_lds_dwordx4 v58, s[0:1]
	v_mfma_f32_16x16x32_bf16 v[44:47], v[144:147], v[164:167], v[44:47]
	v_mfma_f32_16x16x32_bf16 v[36:39], v[144:147], v[168:171], v[36:39]
	s_add_u32 m0, s4, 0xb000
	s_nop 0
	global_load_lds_dwordx4 v59, s[0:1]
	v_mfma_f32_16x16x32_bf16 v[32:35], v[148:151], v[156:159], v[32:35]
	v_mfma_f32_16x16x32_bf16 v[28:31], v[148:151], v[160:163], v[28:31]
	s_add_u32 m0, s4, 0xc000
	s_nop 0
	global_load_lds_dwordx4 v56, s[2:3]
	v_mfma_f32_16x16x32_bf16 v[24:27], v[148:151], v[164:167], v[24:27]
	v_mfma_f32_16x16x32_bf16 v[20:23], v[148:151], v[168:171], v[20:23]
	s_add_u32 m0, s4, 0xd000
	s_nop 0
	global_load_lds_dwordx4 v57, s[2:3]
	v_mfma_f32_16x16x32_bf16 v[16:19], v[152:155], v[156:159], v[16:19]
	v_mfma_f32_16x16x32_bf16 v[12:15], v[152:155], v[160:163], v[12:15]
	s_add_u32 m0, s4, 0xe000
	s_nop 0
	global_load_lds_dwordx4 v58, s[2:3]
	v_mfma_f32_16x16x32_bf16 v[8:11], v[152:155], v[164:167], v[8:11]
	v_mfma_f32_16x16x32_bf16 v[4:7], v[152:155], v[168:171], v[4:7]
	s_add_u32 m0, s4, 0xf000
	s_nop 0
	global_load_lds_dwordx4 v59, s[2:3]
	s_add_u32 s0, s0, 0x80
	s_addc_u32 s1, s1, 0
	s_add_u32 s2, s2, 0x80
	s_addc_u32 s3, s3, 0
	s_waitcnt vmcnt(0) lgkmcnt(0)
	s_barrier
	ds_read_b128 v[140:143], v66 offset:32768
	ds_read_b128 v[144:147], v66 offset:34816
	ds_read_b128 v[148:151], v66 offset:36864
	ds_read_b128 v[152:155], v66 offset:38912
	ds_read_b128 v[156:159], v64 offset:32768
	ds_read_b128 v[160:163], v64 offset:34816
	ds_read_b128 v[164:167], v64 offset:36864
	ds_read_b128 v[168:171], v64 offset:38912
	v_mfma_f32_16x16x32_bf16 v[60:63], v[172:175], v[188:191], v[60:63]
	v_mfma_f32_16x16x32_bf16 v[68:71], v[172:175], v[192:195], v[68:71]
	v_mfma_f32_16x16x32_bf16 v[52:55], v[172:175], v[196:199], v[52:55]
	v_mfma_f32_16x16x32_bf16 v[40:43], v[172:175], v[200:203], v[40:43]
	v_mfma_f32_16x16x32_bf16 v[72:75], v[176:179], v[188:191], v[72:75]
	v_mfma_f32_16x16x32_bf16 v[48:51], v[176:179], v[192:195], v[48:51]
	v_mfma_f32_16x16x32_bf16 v[44:47], v[176:179], v[196:199], v[44:47]
	v_mfma_f32_16x16x32_bf16 v[36:39], v[176:179], v[200:203], v[36:39]
	v_mfma_f32_16x16x32_bf16 v[32:35], v[180:183], v[188:191], v[32:35]
	v_mfma_f32_16x16x32_bf16 v[28:31], v[180:183], v[192:195], v[28:31]
	v_mfma_f32_16x16x32_bf16 v[24:27], v[180:183], v[196:199], v[24:27]
	v_mfma_f32_16x16x32_bf16 v[20:23], v[180:183], v[200:203], v[20:23]
	v_mfma_f32_16x16x32_bf16 v[16:19], v[184:187], v[188:191], v[16:19]
	v_mfma_f32_16x16x32_bf16 v[12:15], v[184:187], v[192:195], v[12:15]
	v_mfma_f32_16x16x32_bf16 v[8:11], v[184:187], v[196:199], v[8:11]
	v_mfma_f32_16x16x32_bf16 v[4:7], v[184:187], v[200:203], v[4:7]
	s_waitcnt lgkmcnt(0)
	ds_read_b128 v[172:175], v67 offset:32768
	ds_read_b128 v[176:179], v67 offset:34816
	ds_read_b128 v[180:183], v67 offset:36864
	ds_read_b128 v[184:187], v67 offset:38912
	ds_read_b128 v[188:191], v65 offset:32768
	ds_read_b128 v[192:195], v65 offset:34816
	ds_read_b128 v[196:199], v65 offset:36864
	ds_read_b128 v[200:203], v65 offset:38912
	v_mfma_f32_16x16x32_bf16 v[60:63], v[140:143], v[156:159], v[60:63]
	v_mfma_f32_16x16x32_bf16 v[68:71], v[140:143], v[160:163], v[68:71]
	s_add_u32 m0, s4, 0x0
	s_nop 0
	global_load_lds_dwordx4 v56, s[0:1]
	v_mfma_f32_16x16x32_bf16 v[52:55], v[140:143], v[164:167], v[52:55]
	v_mfma_f32_16x16x32_bf16 v[40:43], v[140:143], v[168:171], v[40:43]
	s_add_u32 m0, s4, 0x1000
	s_nop 0
	global_load_lds_dwordx4 v57, s[0:1]
	v_mfma_f32_16x16x32_bf16 v[72:75], v[144:147], v[156:159], v[72:75]
	v_mfma_f32_16x16x32_bf16 v[48:51], v[144:147], v[160:163], v[48:51]
	s_add_u32 m0, s4, 0x2000
	s_nop 0
	global_load_lds_dwordx4 v58, s[0:1]
	v_mfma_f32_16x16x32_bf16 v[44:47], v[144:147], v[164:167], v[44:47]
	v_mfma_f32_16x16x32_bf16 v[36:39], v[144:147], v[168:171], v[36:39]
	s_add_u32 m0, s4, 0x3000
	s_nop 0
	global_load_lds_dwordx4 v59, s[0:1]
	v_mfma_f32_16x16x32_bf16 v[32:35], v[148:151], v[156:159], v[32:35]
	v_mfma_f32_16x16x32_bf16 v[28:31], v[148:151], v[160:163], v[28:31]
	s_add_u32 m0, s4, 0x4000
	s_nop 0
	global_load_lds_dwordx4 v56, s[2:3]
	v_mfma_f32_16x16x32_bf16 v[24:27], v[148:151], v[164:167], v[24:27]
	v_mfma_f32_16x16x32_bf16 v[20:23], v[148:151], v[168:171], v[20:23]
	s_add_u32 m0, s4, 0x5000
	s_nop 0
	global_load_lds_dwordx4 v57, s[2:3]
	v_mfma_f32_16x16x32_bf16 v[16:19], v[152:155], v[156:159], v[16:19]
	v_mfma_f32_16x16x32_bf16 v[12:15], v[152:155], v[160:163], v[12:15]
	s_add_u32 m0, s4, 0x6000
	s_nop 0
	global_load_lds_dwordx4 v58, s[2:3]
	v_mfma_f32_16x16x32_bf16 v[8:11], v[152:155], v[164:167], v[8:11]
	v_mfma_f32_16x16x32_bf16 v[4:7], v[152:155], v[168:171], v[4:7]
	s_add_u32 m0, s4, 0x7000
	s_nop 0
	global_load_lds_dwordx4 v59, s[2:3]
	s_add_u32 s0, s0, 0x80
	s_addc_u32 s1, s1, 0
	s_add_u32 s2, s2, 0x80
	s_addc_u32 s3, s3, 0
	s_waitcnt vmcnt(0) lgkmcnt(0)
	s_barrier
	ds_read_b128 v[140:143], v66 offset:0
	ds_read_b128 v[144:147], v66 offset:2048
	ds_read_b128 v[148:151], v66 offset:4096
	ds_read_b128 v[152:155], v66 offset:6144
	ds_read_b128 v[156:159], v64 offset:0
	ds_read_b128 v[160:163], v64 offset:2048
	ds_read_b128 v[164:167], v64 offset:4096
	ds_read_b128 v[168:171], v64 offset:6144
	v_mfma_f32_16x16x32_bf16 v[60:63], v[172:175], v[188:191], v[60:63]
	v_mfma_f32_16x16x32_bf16 v[68:71], v[172:175], v[192:195], v[68:71]
	v_mfma_f32_16x16x32_bf16 v[52:55], v[172:175], v[196:199], v[52:55]
	v_mfma_f32_16x16x32_bf16 v[40:43], v[172:175], v[200:203], v[40:43]
	v_mfma_f32_16x16x32_bf16 v[72:75], v[176:179], v[188:191], v[72:75]
	v_mfma_f32_16x16x32_bf16 v[48:51], v[176:179], v[192:195], v[48:51]
	v_mfma_f32_16x16x32_bf16 v[44:47], v[176:179], v[196:199], v[44:47]
	v_mfma_f32_16x16x32_bf16 v[36:39], v[176:179], v[200:203], v[36:39]
	v_mfma_f32_16x16x32_bf16 v[32:35], v[180:183], v[188:191], v[32:35]
	v_mfma_f32_16x16x32_bf16 v[28:31], v[180:183], v[192:195], v[28:31]
	v_mfma_f32_16x16x32_bf16 v[24:27], v[180:183], v[196:199], v[24:27]
	v_mfma_f32_16x16x32_bf16 v[20:23], v[180:183], v[200:203], v[20:23]
	v_mfma_f32_16x16x32_bf16 v[16:19], v[184:187], v[188:191], v[16:19]
	v_mfma_f32_16x16x32_bf16 v[12:15], v[184:187], v[192:195], v[12:15]
	v_mfma_f32_16x16x32_bf16 v[8:11], v[184:187], v[196:199], v[8:11]
	v_mfma_f32_16x16x32_bf16 v[4:7], v[184:187], v[200:203], v[4:7]
	s_waitcnt lgkmcnt(0)
	ds_read_b128 v[172:175], v67 offset:0
	ds_read_b128 v[176:179], v67 offset:2048
	ds_read_b128 v[180:183], v67 offset:4096
	ds_read_b128 v[184:187], v67 offset:6144
	ds_read_b128 v[188:191], v65 offset:0
	ds_read_b128 v[192:195], v65 offset:2048
	ds_read_b128 v[196:199], v65 offset:4096
	ds_read_b128 v[200:203], v65 offset:6144
	v_mfma_f32_16x16x32_bf16 v[60:63], v[140:143], v[156:159], v[60:63]
	v_mfma_f32_16x16x32_bf16 v[68:71], v[140:143], v[160:163], v[68:71]
	s_add_u32 m0, s4, 0x8000
	s_nop 0
	global_load_lds_dwordx4 v56, s[0:1]
	v_mfma_f32_16x16x32_bf16 v[52:55], v[140:143], v[164:167], v[52:55]
	v_mfma_f32_16x16x32_bf16 v[40:43], v[140:143], v[168:171], v[40:43]
	s_add_u32 m0, s4, 0x9000
	s_nop 0
	global_load_lds_dwordx4 v57, s[0:1]
	v_mfma_f32_16x16x32_bf16 v[72:75], v[144:147], v[156:159], v[72:75]
	v_mfma_f32_16x16x32_bf16 v[48:51], v[144:147], v[160:163], v[48:51]
	s_add_u32 m0, s4, 0xa000
	s_nop 0
	global_load_lds_dwordx4 v58, s[0:1]
	v_mfma_f32_16x16x32_bf16 v[44:47], v[144:147], v[164:167], v[44:47]
	v_mfma_f32_16x16x32_bf16 v[36:39], v[144:147], v[168:171], v[36:39]
	s_add_u32 m0, s4, 0xb000
	s_nop 0
	global_load_lds_dwordx4 v59, s[0:1]
	v_mfma_f32_16x16x32_bf16 v[32:35], v[148:151], v[156:159], v[32:35]
	v_mfma_f32_16x16x32_bf16 v[28:31], v[148:151], v[160:163], v[28:31]
	s_add_u32 m0, s4, 0xc000
	s_nop 0
	global_load_lds_dwordx4 v56, s[2:3]
	v_mfma_f32_16x16x32_bf16 v[24:27], v[148:151], v[164:167], v[24:27]
	v_mfma_f32_16x16x32_bf16 v[20:23], v[148:151], v[168:171], v[20:23]
	s_add_u32 m0, s4, 0xd000
	s_nop 0
	global_load_lds_dwordx4 v57, s[2:3]
	v_mfma_f32_16x16x32_bf16 v[16:19], v[152:155], v[156:159], v[16:19]
	v_mfma_f32_16x16x32_bf16 v[12:15], v[152:155], v[160:163], v[12:15]
	s_add_u32 m0, s4, 0xe000
	s_nop 0
	global_load_lds_dwordx4 v58, s[2:3]
	v_mfma_f32_16x16x32_bf16 v[8:11], v[152:155], v[164:167], v[8:11]
	v_mfma_f32_16x16x32_bf16 v[4:7], v[152:155], v[168:171], v[4:7]
	s_add_u32 m0, s4, 0xf000
	s_nop 0
	global_load_lds_dwordx4 v59, s[2:3]
	s_add_u32 s0, s0, 0x80
	s_addc_u32 s1, s1, 0
	s_add_u32 s2, s2, 0x80
	s_addc_u32 s3, s3, 0
	s_waitcnt vmcnt(0) lgkmcnt(0)
	s_barrier
	ds_read_b128 v[140:143], v66 offset:32768
	ds_read_b128 v[144:147], v66 offset:34816
	ds_read_b128 v[148:151], v66 offset:36864
	ds_read_b128 v[152:155], v66 offset:38912
	ds_read_b128 v[156:159], v64 offset:32768
	ds_read_b128 v[160:163], v64 offset:34816
	ds_read_b128 v[164:167], v64 offset:36864
	ds_read_b128 v[168:171], v64 offset:38912
	v_mfma_f32_16x16x32_bf16 v[60:63], v[172:175], v[188:191], v[60:63]
	v_mfma_f32_16x16x32_bf16 v[68:71], v[172:175], v[192:195], v[68:71]
	v_mfma_f32_16x16x32_bf16 v[52:55], v[172:175], v[196:199], v[52:55]
	v_mfma_f32_16x16x32_bf16 v[40:43], v[172:175], v[200:203], v[40:43]
	v_mfma_f32_16x16x32_bf16 v[72:75], v[176:179], v[188:191], v[72:75]
	v_mfma_f32_16x16x32_bf16 v[48:51], v[176:179], v[192:195], v[48:51]
	v_mfma_f32_16x16x32_bf16 v[44:47], v[176:179], v[196:199], v[44:47]
	v_mfma_f32_16x16x32_bf16 v[36:39], v[176:179], v[200:203], v[36:39]
	v_mfma_f32_16x16x32_bf16 v[32:35], v[180:183], v[188:191], v[32:35]
	v_mfma_f32_16x16x32_bf16 v[28:31], v[180:183], v[192:195], v[28:31]
	v_mfma_f32_16x16x32_bf16 v[24:27], v[180:183], v[196:199], v[24:27]
	v_mfma_f32_16x16x32_bf16 v[20:23], v[180:183], v[200:203], v[20:23]
	v_mfma_f32_16x16x32_bf16 v[16:19], v[184:187], v[188:191], v[16:19]
	v_mfma_f32_16x16x32_bf16 v[12:15], v[184:187], v[192:195], v[12:15]
	v_mfma_f32_16x16x32_bf16 v[8:11], v[184:187], v[196:199], v[8:11]
	v_mfma_f32_16x16x32_bf16 v[4:7], v[184:187], v[200:203], v[4:7]
	s_waitcnt lgkmcnt(0)
	ds_read_b128 v[172:175], v67 offset:32768
	ds_read_b128 v[176:179], v67 offset:34816
	ds_read_b128 v[180:183], v67 offset:36864
	ds_read_b128 v[184:187], v67 offset:38912
	ds_read_b128 v[188:191], v65 offset:32768
	ds_read_b128 v[192:195], v65 offset:34816
	ds_read_b128 v[196:199], v65 offset:36864
	ds_read_b128 v[200:203], v65 offset:38912
	v_mfma_f32_16x16x32_bf16 v[60:63], v[140:143], v[156:159], v[60:63]
	v_mfma_f32_16x16x32_bf16 v[68:71], v[140:143], v[160:163], v[68:71]
	s_add_u32 m0, s4, 0x0
	s_nop 0
	global_load_lds_dwordx4 v56, s[0:1]
	v_mfma_f32_16x16x32_bf16 v[52:55], v[140:143], v[164:167], v[52:55]
	v_mfma_f32_16x16x32_bf16 v[40:43], v[140:143], v[168:171], v[40:43]
	s_add_u32 m0, s4, 0x1000
	s_nop 0
	global_load_lds_dwordx4 v57, s[0:1]
	v_mfma_f32_16x16x32_bf16 v[72:75], v[144:147], v[156:159], v[72:75]
	v_mfma_f32_16x16x32_bf16 v[48:51], v[144:147], v[160:163], v[48:51]
	s_add_u32 m0, s4, 0x2000
	s_nop 0
	global_load_lds_dwordx4 v58, s[0:1]
	v_mfma_f32_16x16x32_bf16 v[44:47], v[144:147], v[164:167], v[44:47]
	v_mfma_f32_16x16x32_bf16 v[36:39], v[144:147], v[168:171], v[36:39]
	s_add_u32 m0, s4, 0x3000
	s_nop 0
	global_load_lds_dwordx4 v59, s[0:1]
	v_mfma_f32_16x16x32_bf16 v[32:35], v[148:151], v[156:159], v[32:35]
	v_mfma_f32_16x16x32_bf16 v[28:31], v[148:151], v[160:163], v[28:31]
	s_add_u32 m0, s4, 0x4000
	s_nop 0
	global_load_lds_dwordx4 v56, s[2:3]
	v_mfma_f32_16x16x32_bf16 v[24:27], v[148:151], v[164:167], v[24:27]
	v_mfma_f32_16x16x32_bf16 v[20:23], v[148:151], v[168:171], v[20:23]
	s_add_u32 m0, s4, 0x5000
	s_nop 0
	global_load_lds_dwordx4 v57, s[2:3]
	v_mfma_f32_16x16x32_bf16 v[16:19], v[152:155], v[156:159], v[16:19]
	v_mfma_f32_16x16x32_bf16 v[12:15], v[152:155], v[160:163], v[12:15]
	s_add_u32 m0, s4, 0x6000
	s_nop 0
	global_load_lds_dwordx4 v58, s[2:3]
	v_mfma_f32_16x16x32_bf16 v[8:11], v[152:155], v[164:167], v[8:11]
	v_mfma_f32_16x16x32_bf16 v[4:7], v[152:155], v[168:171], v[4:7]
	s_add_u32 m0, s4, 0x7000
	s_nop 0
	global_load_lds_dwordx4 v59, s[2:3]
	s_add_u32 s0, s0, 0x80
	s_addc_u32 s1, s1, 0
	s_add_u32 s2, s2, 0x80
	s_addc_u32 s3, s3, 0
	s_waitcnt vmcnt(0) lgkmcnt(0)
	s_barrier
	ds_read_b128 v[140:143], v66 offset:0
	ds_read_b128 v[144:147], v66 offset:2048
	ds_read_b128 v[148:151], v66 offset:4096
	ds_read_b128 v[152:155], v66 offset:6144
	ds_read_b128 v[156:159], v64 offset:0
	ds_read_b128 v[160:163], v64 offset:2048
	ds_read_b128 v[164:167], v64 offset:4096
	ds_read_b128 v[168:171], v64 offset:6144
	v_mfma_f32_16x16x32_bf16 v[60:63], v[172:175], v[188:191], v[60:63]
	v_mfma_f32_16x16x32_bf16 v[68:71], v[172:175], v[192:195], v[68:71]
	v_mfma_f32_16x16x32_bf16 v[52:55], v[172:175], v[196:199], v[52:55]
	v_mfma_f32_16x16x32_bf16 v[40:43], v[172:175], v[200:203], v[40:43]
	v_mfma_f32_16x16x32_bf16 v[72:75], v[176:179], v[188:191], v[72:75]
	v_mfma_f32_16x16x32_bf16 v[48:51], v[176:179], v[192:195], v[48:51]
	v_mfma_f32_16x16x32_bf16 v[44:47], v[176:179], v[196:199], v[44:47]
	v_mfma_f32_16x16x32_bf16 v[36:39], v[176:179], v[200:203], v[36:39]
	v_mfma_f32_16x16x32_bf16 v[32:35], v[180:183], v[188:191], v[32:35]
	v_mfma_f32_16x16x32_bf16 v[28:31], v[180:183], v[192:195], v[28:31]
	v_mfma_f32_16x16x32_bf16 v[24:27], v[180:183], v[196:199], v[24:27]
	v_mfma_f32_16x16x32_bf16 v[20:23], v[180:183], v[200:203], v[20:23]
	v_mfma_f32_16x16x32_bf16 v[16:19], v[184:187], v[188:191], v[16:19]
	v_mfma_f32_16x16x32_bf16 v[12:15], v[184:187], v[192:195], v[12:15]
	v_mfma_f32_16x16x32_bf16 v[8:11], v[184:187], v[196:199], v[8:11]
	v_mfma_f32_16x16x32_bf16 v[4:7], v[184:187], v[200:203], v[4:7]
	s_waitcnt lgkmcnt(0)
	ds_read_b128 v[172:175], v67 offset:0
	ds_read_b128 v[176:179], v67 offset:2048
	ds_read_b128 v[180:183], v67 offset:4096
	ds_read_b128 v[184:187], v67 offset:6144
	ds_read_b128 v[188:191], v65 offset:0
	ds_read_b128 v[192:195], v65 offset:2048
	ds_read_b128 v[196:199], v65 offset:4096
	ds_read_b128 v[200:203], v65 offset:6144
	v_mfma_f32_16x16x32_bf16 v[60:63], v[140:143], v[156:159], v[60:63]
	v_mfma_f32_16x16x32_bf16 v[68:71], v[140:143], v[160:163], v[68:71]
	s_add_u32 m0, s4, 0x8000
	s_nop 0
	global_load_lds_dwordx4 v56, s[0:1]
	v_mfma_f32_16x16x32_bf16 v[52:55], v[140:143], v[164:167], v[52:55]
	v_mfma_f32_16x16x32_bf16 v[40:43], v[140:143], v[168:171], v[40:43]
	s_add_u32 m0, s4, 0x9000
	s_nop 0
	global_load_lds_dwordx4 v57, s[0:1]
	v_mfma_f32_16x16x32_bf16 v[72:75], v[144:147], v[156:159], v[72:75]
	v_mfma_f32_16x16x32_bf16 v[48:51], v[144:147], v[160:163], v[48:51]
	s_add_u32 m0, s4, 0xa000
	s_nop 0
	global_load_lds_dwordx4 v58, s[0:1]
	v_mfma_f32_16x16x32_bf16 v[44:47], v[144:147], v[164:167], v[44:47]
	v_mfma_f32_16x16x32_bf16 v[36:39], v[144:147], v[168:171], v[36:39]
	s_add_u32 m0, s4, 0xb000
	s_nop 0
	global_load_lds_dwordx4 v59, s[0:1]
	v_mfma_f32_16x16x32_bf16 v[32:35], v[148:151], v[156:159], v[32:35]
	v_mfma_f32_16x16x32_bf16 v[28:31], v[148:151], v[160:163], v[28:31]
	s_add_u32 m0, s4, 0xc000
	s_nop 0
	global_load_lds_dwordx4 v56, s[2:3]
	v_mfma_f32_16x16x32_bf16 v[24:27], v[148:151], v[164:167], v[24:27]
	v_mfma_f32_16x16x32_bf16 v[20:23], v[148:151], v[168:171], v[20:23]
	s_add_u32 m0, s4, 0xd000
	s_nop 0
	global_load_lds_dwordx4 v57, s[2:3]
	v_mfma_f32_16x16x32_bf16 v[16:19], v[152:155], v[156:159], v[16:19]
	v_mfma_f32_16x16x32_bf16 v[12:15], v[152:155], v[160:163], v[12:15]
	s_add_u32 m0, s4, 0xe000
	s_nop 0
	global_load_lds_dwordx4 v58, s[2:3]
	v_mfma_f32_16x16x32_bf16 v[8:11], v[152:155], v[164:167], v[8:11]
	v_mfma_f32_16x16x32_bf16 v[4:7], v[152:155], v[168:171], v[4:7]
	s_add_u32 m0, s4, 0xf000
	s_nop 0
	global_load_lds_dwordx4 v59, s[2:3]
	s_add_u32 s0, s0, 0x80
	s_addc_u32 s1, s1, 0
	s_add_u32 s2, s2, 0x80
	s_addc_u32 s3, s3, 0
	s_waitcnt vmcnt(0) lgkmcnt(0)
	s_barrier
	ds_read_b128 v[140:143], v66 offset:32768
	ds_read_b128 v[144:147], v66 offset:34816
	ds_read_b128 v[148:151], v66 offset:36864
	ds_read_b128 v[152:155], v66 offset:38912
	ds_read_b128 v[156:159], v64 offset:32768
	ds_read_b128 v[160:163], v64 offset:34816
	ds_read_b128 v[164:167], v64 offset:36864
	ds_read_b128 v[168:171], v64 offset:38912
	v_mfma_f32_16x16x32_bf16 v[60:63], v[172:175], v[188:191], v[60:63]
	v_mfma_f32_16x16x32_bf16 v[68:71], v[172:175], v[192:195], v[68:71]
	v_mfma_f32_16x16x32_bf16 v[52:55], v[172:175], v[196:199], v[52:55]
	v_mfma_f32_16x16x32_bf16 v[40:43], v[172:175], v[200:203], v[40:43]
	v_mfma_f32_16x16x32_bf16 v[72:75], v[176:179], v[188:191], v[72:75]
	v_mfma_f32_16x16x32_bf16 v[48:51], v[176:179], v[192:195], v[48:51]
	v_mfma_f32_16x16x32_bf16 v[44:47], v[176:179], v[196:199], v[44:47]
	v_mfma_f32_16x16x32_bf16 v[36:39], v[176:179], v[200:203], v[36:39]
	v_mfma_f32_16x16x32_bf16 v[32:35], v[180:183], v[188:191], v[32:35]
	v_mfma_f32_16x16x32_bf16 v[28:31], v[180:183], v[192:195], v[28:31]
	v_mfma_f32_16x16x32_bf16 v[24:27], v[180:183], v[196:199], v[24:27]
	v_mfma_f32_16x16x32_bf16 v[20:23], v[180:183], v[200:203], v[20:23]
	v_mfma_f32_16x16x32_bf16 v[16:19], v[184:187], v[188:191], v[16:19]
	v_mfma_f32_16x16x32_bf16 v[12:15], v[184:187], v[192:195], v[12:15]
	v_mfma_f32_16x16x32_bf16 v[8:11], v[184:187], v[196:199], v[8:11]
	v_mfma_f32_16x16x32_bf16 v[4:7], v[184:187], v[200:203], v[4:7]
	s_waitcnt lgkmcnt(0)
	ds_read_b128 v[172:175], v67 offset:32768
	ds_read_b128 v[176:179], v67 offset:34816
	ds_read_b128 v[180:183], v67 offset:36864
	ds_read_b128 v[184:187], v67 offset:38912
	ds_read_b128 v[188:191], v65 offset:32768
	ds_read_b128 v[192:195], v65 offset:34816
	ds_read_b128 v[196:199], v65 offset:36864
	ds_read_b128 v[200:203], v65 offset:38912
	v_mfma_f32_16x16x32_bf16 v[60:63], v[140:143], v[156:159], v[60:63]
	v_mfma_f32_16x16x32_bf16 v[68:71], v[140:143], v[160:163], v[68:71]
	s_add_u32 m0, s4, 0x0
	s_nop 0
	global_load_lds_dwordx4 v56, s[0:1]
	v_mfma_f32_16x16x32_bf16 v[52:55], v[140:143], v[164:167], v[52:55]
	v_mfma_f32_16x16x32_bf16 v[40:43], v[140:143], v[168:171], v[40:43]
	s_add_u32 m0, s4, 0x1000
	s_nop 0
	global_load_lds_dwordx4 v57, s[0:1]
	v_mfma_f32_16x16x32_bf16 v[72:75], v[144:147], v[156:159], v[72:75]
	v_mfma_f32_16x16x32_bf16 v[48:51], v[144:147], v[160:163], v[48:51]
	s_add_u32 m0, s4, 0x2000
	s_nop 0
	global_load_lds_dwordx4 v58, s[0:1]
	v_mfma_f32_16x16x32_bf16 v[44:47], v[144:147], v[164:167], v[44:47]
	v_mfma_f32_16x16x32_bf16 v[36:39], v[144:147], v[168:171], v[36:39]
	s_add_u32 m0, s4, 0x3000
	s_nop 0
	global_load_lds_dwordx4 v59, s[0:1]
	v_mfma_f32_16x16x32_bf16 v[32:35], v[148:151], v[156:159], v[32:35]
	v_mfma_f32_16x16x32_bf16 v[28:31], v[148:151], v[160:163], v[28:31]
	s_add_u32 m0, s4, 0x4000
	s_nop 0
	global_load_lds_dwordx4 v56, s[2:3]
	v_mfma_f32_16x16x32_bf16 v[24:27], v[148:151], v[164:167], v[24:27]
	v_mfma_f32_16x16x32_bf16 v[20:23], v[148:151], v[168:171], v[20:23]
	s_add_u32 m0, s4, 0x5000
	s_nop 0
	global_load_lds_dwordx4 v57, s[2:3]
	v_mfma_f32_16x16x32_bf16 v[16:19], v[152:155], v[156:159], v[16:19]
	v_mfma_f32_16x16x32_bf16 v[12:15], v[152:155], v[160:163], v[12:15]
	s_add_u32 m0, s4, 0x6000
	s_nop 0
	global_load_lds_dwordx4 v58, s[2:3]
	v_mfma_f32_16x16x32_bf16 v[8:11], v[152:155], v[164:167], v[8:11]
	v_mfma_f32_16x16x32_bf16 v[4:7], v[152:155], v[168:171], v[4:7]
	s_add_u32 m0, s4, 0x7000
	s_nop 0
	global_load_lds_dwordx4 v59, s[2:3]
	s_add_u32 s0, s0, 0x80
	s_addc_u32 s1, s1, 0
	s_add_u32 s2, s2, 0x80
	s_addc_u32 s3, s3, 0
	s_waitcnt vmcnt(0) lgkmcnt(0)
	s_barrier
	ds_read_b128 v[140:143], v66 offset:0
	ds_read_b128 v[144:147], v66 offset:2048
	ds_read_b128 v[148:151], v66 offset:4096
	ds_read_b128 v[152:155], v66 offset:6144
	ds_read_b128 v[156:159], v64 offset:0
	ds_read_b128 v[160:163], v64 offset:2048
	ds_read_b128 v[164:167], v64 offset:4096
	ds_read_b128 v[168:171], v64 offset:6144
	v_mfma_f32_16x16x32_bf16 v[60:63], v[172:175], v[188:191], v[60:63]
	v_mfma_f32_16x16x32_bf16 v[68:71], v[172:175], v[192:195], v[68:71]
	v_mfma_f32_16x16x32_bf16 v[52:55], v[172:175], v[196:199], v[52:55]
	v_mfma_f32_16x16x32_bf16 v[40:43], v[172:175], v[200:203], v[40:43]
	v_mfma_f32_16x16x32_bf16 v[72:75], v[176:179], v[188:191], v[72:75]
	v_mfma_f32_16x16x32_bf16 v[48:51], v[176:179], v[192:195], v[48:51]
	v_mfma_f32_16x16x32_bf16 v[44:47], v[176:179], v[196:199], v[44:47]
	v_mfma_f32_16x16x32_bf16 v[36:39], v[176:179], v[200:203], v[36:39]
	v_mfma_f32_16x16x32_bf16 v[32:35], v[180:183], v[188:191], v[32:35]
	v_mfma_f32_16x16x32_bf16 v[28:31], v[180:183], v[192:195], v[28:31]
	v_mfma_f32_16x16x32_bf16 v[24:27], v[180:183], v[196:199], v[24:27]
	v_mfma_f32_16x16x32_bf16 v[20:23], v[180:183], v[200:203], v[20:23]
	v_mfma_f32_16x16x32_bf16 v[16:19], v[184:187], v[188:191], v[16:19]
	v_mfma_f32_16x16x32_bf16 v[12:15], v[184:187], v[192:195], v[12:15]
	v_mfma_f32_16x16x32_bf16 v[8:11], v[184:187], v[196:199], v[8:11]
	v_mfma_f32_16x16x32_bf16 v[4:7], v[184:187], v[200:203], v[4:7]
	s_waitcnt lgkmcnt(0)
	ds_read_b128 v[172:175], v67 offset:0
	ds_read_b128 v[176:179], v67 offset:2048
	ds_read_b128 v[180:183], v67 offset:4096
	ds_read_b128 v[184:187], v67 offset:6144
	ds_read_b128 v[188:191], v65 offset:0
	ds_read_b128 v[192:195], v65 offset:2048
	ds_read_b128 v[196:199], v65 offset:4096
	ds_read_b128 v[200:203], v65 offset:6144
	v_mfma_f32_16x16x32_bf16 v[60:63], v[140:143], v[156:159], v[60:63]
	v_mfma_f32_16x16x32_bf16 v[68:71], v[140:143], v[160:163], v[68:71]
	s_add_u32 m0, s4, 0x8000
	s_nop 0
	global_load_lds_dwordx4 v56, s[0:1]
	v_mfma_f32_16x16x32_bf16 v[52:55], v[140:143], v[164:167], v[52:55]
	v_mfma_f32_16x16x32_bf16 v[40:43], v[140:143], v[168:171], v[40:43]
	s_add_u32 m0, s4, 0x9000
	s_nop 0
	global_load_lds_dwordx4 v57, s[0:1]
	v_mfma_f32_16x16x32_bf16 v[72:75], v[144:147], v[156:159], v[72:75]
	v_mfma_f32_16x16x32_bf16 v[48:51], v[144:147], v[160:163], v[48:51]
	s_add_u32 m0, s4, 0xa000
	s_nop 0
	global_load_lds_dwordx4 v58, s[0:1]
	v_mfma_f32_16x16x32_bf16 v[44:47], v[144:147], v[164:167], v[44:47]
	v_mfma_f32_16x16x32_bf16 v[36:39], v[144:147], v[168:171], v[36:39]
	s_add_u32 m0, s4, 0xb000
	s_nop 0
	global_load_lds_dwordx4 v59, s[0:1]
	v_mfma_f32_16x16x32_bf16 v[32:35], v[148:151], v[156:159], v[32:35]
	v_mfma_f32_16x16x32_bf16 v[28:31], v[148:151], v[160:163], v[28:31]
	s_add_u32 m0, s4, 0xc000
	s_nop 0
	global_load_lds_dwordx4 v56, s[2:3]
	v_mfma_f32_16x16x32_bf16 v[24:27], v[148:151], v[164:167], v[24:27]
	v_mfma_f32_16x16x32_bf16 v[20:23], v[148:151], v[168:171], v[20:23]
	s_add_u32 m0, s4, 0xd000
	s_nop 0
	global_load_lds_dwordx4 v57, s[2:3]
	v_mfma_f32_16x16x32_bf16 v[16:19], v[152:155], v[156:159], v[16:19]
	v_mfma_f32_16x16x32_bf16 v[12:15], v[152:155], v[160:163], v[12:15]
	s_add_u32 m0, s4, 0xe000
	s_nop 0
	global_load_lds_dwordx4 v58, s[2:3]
	v_mfma_f32_16x16x32_bf16 v[8:11], v[152:155], v[164:167], v[8:11]
	v_mfma_f32_16x16x32_bf16 v[4:7], v[152:155], v[168:171], v[4:7]
	s_add_u32 m0, s4, 0xf000
	s_nop 0
	global_load_lds_dwordx4 v59, s[2:3]
	s_add_u32 s0, s0, 0x80
	s_addc_u32 s1, s1, 0
	s_add_u32 s2, s2, 0x80
	s_addc_u32 s3, s3, 0
	s_waitcnt vmcnt(0) lgkmcnt(0)
	s_barrier
	ds_read_b128 v[140:143], v66 offset:32768
	ds_read_b128 v[144:147], v66 offset:34816
	ds_read_b128 v[148:151], v66 offset:36864
	ds_read_b128 v[152:155], v66 offset:38912
	ds_read_b128 v[156:159], v64 offset:32768
	ds_read_b128 v[160:163], v64 offset:34816
	ds_read_b128 v[164:167], v64 offset:36864
	ds_read_b128 v[168:171], v64 offset:38912
	v_mfma_f32_16x16x32_bf16 v[60:63], v[172:175], v[188:191], v[60:63]
	v_mfma_f32_16x16x32_bf16 v[68:71], v[172:175], v[192:195], v[68:71]
	v_mfma_f32_16x16x32_bf16 v[52:55], v[172:175], v[196:199], v[52:55]
	v_mfma_f32_16x16x32_bf16 v[40:43], v[172:175], v[200:203], v[40:43]
	v_mfma_f32_16x16x32_bf16 v[72:75], v[176:179], v[188:191], v[72:75]
	v_mfma_f32_16x16x32_bf16 v[48:51], v[176:179], v[192:195], v[48:51]
	v_mfma_f32_16x16x32_bf16 v[44:47], v[176:179], v[196:199], v[44:47]
	v_mfma_f32_16x16x32_bf16 v[36:39], v[176:179], v[200:203], v[36:39]
	v_mfma_f32_16x16x32_bf16 v[32:35], v[180:183], v[188:191], v[32:35]
	v_mfma_f32_16x16x32_bf16 v[28:31], v[180:183], v[192:195], v[28:31]
	v_mfma_f32_16x16x32_bf16 v[24:27], v[180:183], v[196:199], v[24:27]
	v_mfma_f32_16x16x32_bf16 v[20:23], v[180:183], v[200:203], v[20:23]
	v_mfma_f32_16x16x32_bf16 v[16:19], v[184:187], v[188:191], v[16:19]
	v_mfma_f32_16x16x32_bf16 v[12:15], v[184:187], v[192:195], v[12:15]
	v_mfma_f32_16x16x32_bf16 v[8:11], v[184:187], v[196:199], v[8:11]
	v_mfma_f32_16x16x32_bf16 v[4:7], v[184:187], v[200:203], v[4:7]
	s_waitcnt lgkmcnt(0)
	ds_read_b128 v[172:175], v67 offset:32768
	ds_read_b128 v[176:179], v67 offset:34816
	ds_read_b128 v[180:183], v67 offset:36864
	ds_read_b128 v[184:187], v67 offset:38912
	ds_read_b128 v[188:191], v65 offset:32768
	ds_read_b128 v[192:195], v65 offset:34816
	ds_read_b128 v[196:199], v65 offset:36864
	ds_read_b128 v[200:203], v65 offset:38912
	v_mfma_f32_16x16x32_bf16 v[60:63], v[140:143], v[156:159], v[60:63]
	v_mfma_f32_16x16x32_bf16 v[68:71], v[140:143], v[160:163], v[68:71]
	s_add_u32 m0, s4, 0x0
	s_nop 0
	global_load_lds_dwordx4 v56, s[0:1]
	v_mfma_f32_16x16x32_bf16 v[52:55], v[140:143], v[164:167], v[52:55]
	v_mfma_f32_16x16x32_bf16 v[40:43], v[140:143], v[168:171], v[40:43]
	s_add_u32 m0, s4, 0x1000
	s_nop 0
	global_load_lds_dwordx4 v57, s[0:1]
	v_mfma_f32_16x16x32_bf16 v[72:75], v[144:147], v[156:159], v[72:75]
	v_mfma_f32_16x16x32_bf16 v[48:51], v[144:147], v[160:163], v[48:51]
	s_add_u32 m0, s4, 0x2000
	s_nop 0
	global_load_lds_dwordx4 v58, s[0:1]
	v_mfma_f32_16x16x32_bf16 v[44:47], v[144:147], v[164:167], v[44:47]
	v_mfma_f32_16x16x32_bf16 v[36:39], v[144:147], v[168:171], v[36:39]
	s_add_u32 m0, s4, 0x3000
	s_nop 0
	global_load_lds_dwordx4 v59, s[0:1]
	v_mfma_f32_16x16x32_bf16 v[32:35], v[148:151], v[156:159], v[32:35]
	v_mfma_f32_16x16x32_bf16 v[28:31], v[148:151], v[160:163], v[28:31]
	s_add_u32 m0, s4, 0x4000
	s_nop 0
	global_load_lds_dwordx4 v56, s[2:3]
	v_mfma_f32_16x16x32_bf16 v[24:27], v[148:151], v[164:167], v[24:27]
	v_mfma_f32_16x16x32_bf16 v[20:23], v[148:151], v[168:171], v[20:23]
	s_add_u32 m0, s4, 0x5000
	s_nop 0
	global_load_lds_dwordx4 v57, s[2:3]
	v_mfma_f32_16x16x32_bf16 v[16:19], v[152:155], v[156:159], v[16:19]
	v_mfma_f32_16x16x32_bf16 v[12:15], v[152:155], v[160:163], v[12:15]
	s_add_u32 m0, s4, 0x6000
	s_nop 0
	global_load_lds_dwordx4 v58, s[2:3]
	v_mfma_f32_16x16x32_bf16 v[8:11], v[152:155], v[164:167], v[8:11]
	v_mfma_f32_16x16x32_bf16 v[4:7], v[152:155], v[168:171], v[4:7]
	s_add_u32 m0, s4, 0x7000
	s_nop 0
	global_load_lds_dwordx4 v59, s[2:3]
	s_add_u32 s0, s0, 0x80
	s_addc_u32 s1, s1, 0
	s_add_u32 s2, s2, 0x80
	s_addc_u32 s3, s3, 0
	s_waitcnt vmcnt(0) lgkmcnt(0)
	s_barrier
	ds_read_b128 v[140:143], v66 offset:0
	ds_read_b128 v[144:147], v66 offset:2048
	ds_read_b128 v[148:151], v66 offset:4096
	ds_read_b128 v[152:155], v66 offset:6144
	ds_read_b128 v[156:159], v64 offset:0
	ds_read_b128 v[160:163], v64 offset:2048
	ds_read_b128 v[164:167], v64 offset:4096
	ds_read_b128 v[168:171], v64 offset:6144
	v_mfma_f32_16x16x32_bf16 v[60:63], v[172:175], v[188:191], v[60:63]
	v_mfma_f32_16x16x32_bf16 v[68:71], v[172:175], v[192:195], v[68:71]
	v_mfma_f32_16x16x32_bf16 v[52:55], v[172:175], v[196:199], v[52:55]
	v_mfma_f32_16x16x32_bf16 v[40:43], v[172:175], v[200:203], v[40:43]
	v_mfma_f32_16x16x32_bf16 v[72:75], v[176:179], v[188:191], v[72:75]
	v_mfma_f32_16x16x32_bf16 v[48:51], v[176:179], v[192:195], v[48:51]
	v_mfma_f32_16x16x32_bf16 v[44:47], v[176:179], v[196:199], v[44:47]
	v_mfma_f32_16x16x32_bf16 v[36:39], v[176:179], v[200:203], v[36:39]
	v_mfma_f32_16x16x32_bf16 v[32:35], v[180:183], v[188:191], v[32:35]
	v_mfma_f32_16x16x32_bf16 v[28:31], v[180:183], v[192:195], v[28:31]
	v_mfma_f32_16x16x32_bf16 v[24:27], v[180:183], v[196:199], v[24:27]
	v_mfma_f32_16x16x32_bf16 v[20:23], v[180:183], v[200:203], v[20:23]
	v_mfma_f32_16x16x32_bf16 v[16:19], v[184:187], v[188:191], v[16:19]
	v_mfma_f32_16x16x32_bf16 v[12:15], v[184:187], v[192:195], v[12:15]
	v_mfma_f32_16x16x32_bf16 v[8:11], v[184:187], v[196:199], v[8:11]
	v_mfma_f32_16x16x32_bf16 v[4:7], v[184:187], v[200:203], v[4:7]
	s_waitcnt lgkmcnt(0)
	ds_read_b128 v[172:175], v67 offset:0
	ds_read_b128 v[176:179], v67 offset:2048
	ds_read_b128 v[180:183], v67 offset:4096
	ds_read_b128 v[184:187], v67 offset:6144
	ds_read_b128 v[188:191], v65 offset:0
	ds_read_b128 v[192:195], v65 offset:2048
	ds_read_b128 v[196:199], v65 offset:4096
	ds_read_b128 v[200:203], v65 offset:6144
	v_mfma_f32_16x16x32_bf16 v[60:63], v[140:143], v[156:159], v[60:63]
	v_mfma_f32_16x16x32_bf16 v[68:71], v[140:143], v[160:163], v[68:71]
	s_add_u32 m0, s4, 0x8000
	s_nop 0
	global_load_lds_dwordx4 v56, s[0:1]
	v_mfma_f32_16x16x32_bf16 v[52:55], v[140:143], v[164:167], v[52:55]
	v_mfma_f32_16x16x32_bf16 v[40:43], v[140:143], v[168:171], v[40:43]
	s_add_u32 m0, s4, 0x9000
	s_nop 0
	global_load_lds_dwordx4 v57, s[0:1]
	v_mfma_f32_16x16x32_bf16 v[72:75], v[144:147], v[156:159], v[72:75]
	v_mfma_f32_16x16x32_bf16 v[48:51], v[144:147], v[160:163], v[48:51]
	s_add_u32 m0, s4, 0xa000
	s_nop 0
	global_load_lds_dwordx4 v58, s[0:1]
	v_mfma_f32_16x16x32_bf16 v[44:47], v[144:147], v[164:167], v[44:47]
	v_mfma_f32_16x16x32_bf16 v[36:39], v[144:147], v[168:171], v[36:39]
	s_add_u32 m0, s4, 0xb000
	s_nop 0
	global_load_lds_dwordx4 v59, s[0:1]
	v_mfma_f32_16x16x32_bf16 v[32:35], v[148:151], v[156:159], v[32:35]
	v_mfma_f32_16x16x32_bf16 v[28:31], v[148:151], v[160:163], v[28:31]
	s_add_u32 m0, s4, 0xc000
	s_nop 0
	global_load_lds_dwordx4 v56, s[2:3]
	v_mfma_f32_16x16x32_bf16 v[24:27], v[148:151], v[164:167], v[24:27]
	v_mfma_f32_16x16x32_bf16 v[20:23], v[148:151], v[168:171], v[20:23]
	s_add_u32 m0, s4, 0xd000
	s_nop 0
	global_load_lds_dwordx4 v57, s[2:3]
	v_mfma_f32_16x16x32_bf16 v[16:19], v[152:155], v[156:159], v[16:19]
	v_mfma_f32_16x16x32_bf16 v[12:15], v[152:155], v[160:163], v[12:15]
	s_add_u32 m0, s4, 0xe000
	s_nop 0
	global_load_lds_dwordx4 v58, s[2:3]
	v_mfma_f32_16x16x32_bf16 v[8:11], v[152:155], v[164:167], v[8:11]
	v_mfma_f32_16x16x32_bf16 v[4:7], v[152:155], v[168:171], v[4:7]
	s_add_u32 m0, s4, 0xf000
	s_nop 0
	global_load_lds_dwordx4 v59, s[2:3]
	s_add_u32 s0, s0, 0x80
	s_addc_u32 s1, s1, 0
	s_add_u32 s2, s2, 0x80
	s_addc_u32 s3, s3, 0
	s_waitcnt vmcnt(0) lgkmcnt(0)
	s_barrier
	ds_read_b128 v[140:143], v66 offset:32768
	ds_read_b128 v[144:147], v66 offset:34816
	ds_read_b128 v[148:151], v66 offset:36864
	ds_read_b128 v[152:155], v66 offset:38912
	ds_read_b128 v[156:159], v64 offset:32768
	ds_read_b128 v[160:163], v64 offset:34816
	ds_read_b128 v[164:167], v64 offset:36864
	ds_read_b128 v[168:171], v64 offset:38912
	v_mfma_f32_16x16x32_bf16 v[60:63], v[172:175], v[188:191], v[60:63]
	v_mfma_f32_16x16x32_bf16 v[68:71], v[172:175], v[192:195], v[68:71]
	v_mfma_f32_16x16x32_bf16 v[52:55], v[172:175], v[196:199], v[52:55]
	v_mfma_f32_16x16x32_bf16 v[40:43], v[172:175], v[200:203], v[40:43]
	v_mfma_f32_16x16x32_bf16 v[72:75], v[176:179], v[188:191], v[72:75]
	v_mfma_f32_16x16x32_bf16 v[48:51], v[176:179], v[192:195], v[48:51]
	v_mfma_f32_16x16x32_bf16 v[44:47], v[176:179], v[196:199], v[44:47]
	v_mfma_f32_16x16x32_bf16 v[36:39], v[176:179], v[200:203], v[36:39]
	v_mfma_f32_16x16x32_bf16 v[32:35], v[180:183], v[188:191], v[32:35]
	v_mfma_f32_16x16x32_bf16 v[28:31], v[180:183], v[192:195], v[28:31]
	v_mfma_f32_16x16x32_bf16 v[24:27], v[180:183], v[196:199], v[24:27]
	v_mfma_f32_16x16x32_bf16 v[20:23], v[180:183], v[200:203], v[20:23]
	v_mfma_f32_16x16x32_bf16 v[16:19], v[184:187], v[188:191], v[16:19]
	v_mfma_f32_16x16x32_bf16 v[12:15], v[184:187], v[192:195], v[12:15]
	v_mfma_f32_16x16x32_bf16 v[8:11], v[184:187], v[196:199], v[8:11]
	v_mfma_f32_16x16x32_bf16 v[4:7], v[184:187], v[200:203], v[4:7]
	s_waitcnt lgkmcnt(0)
	ds_read_b128 v[172:175], v67 offset:32768
	ds_read_b128 v[176:179], v67 offset:34816
	ds_read_b128 v[180:183], v67 offset:36864
	ds_read_b128 v[184:187], v67 offset:38912
	ds_read_b128 v[188:191], v65 offset:32768
	ds_read_b128 v[192:195], v65 offset:34816
	ds_read_b128 v[196:199], v65 offset:36864
	ds_read_b128 v[200:203], v65 offset:38912
	v_mfma_f32_16x16x32_bf16 v[60:63], v[140:143], v[156:159], v[60:63]
	v_mfma_f32_16x16x32_bf16 v[68:71], v[140:143], v[160:163], v[68:71]
	s_add_u32 m0, s4, 0x0
	s_nop 0
	global_load_lds_dwordx4 v56, s[0:1]
	v_mfma_f32_16x16x32_bf16 v[52:55], v[140:143], v[164:167], v[52:55]
	v_mfma_f32_16x16x32_bf16 v[40:43], v[140:143], v[168:171], v[40:43]
	s_add_u32 m0, s4, 0x1000
	s_nop 0
	global_load_lds_dwordx4 v57, s[0:1]
	v_mfma_f32_16x16x32_bf16 v[72:75], v[144:147], v[156:159], v[72:75]
	v_mfma_f32_16x16x32_bf16 v[48:51], v[144:147], v[160:163], v[48:51]
	s_add_u32 m0, s4, 0x2000
	s_nop 0
	global_load_lds_dwordx4 v58, s[0:1]
	v_mfma_f32_16x16x32_bf16 v[44:47], v[144:147], v[164:167], v[44:47]
	v_mfma_f32_16x16x32_bf16 v[36:39], v[144:147], v[168:171], v[36:39]
	s_add_u32 m0, s4, 0x3000
	s_nop 0
	global_load_lds_dwordx4 v59, s[0:1]
	v_mfma_f32_16x16x32_bf16 v[32:35], v[148:151], v[156:159], v[32:35]
	v_mfma_f32_16x16x32_bf16 v[28:31], v[148:151], v[160:163], v[28:31]
	s_add_u32 m0, s4, 0x4000
	s_nop 0
	global_load_lds_dwordx4 v56, s[2:3]
	v_mfma_f32_16x16x32_bf16 v[24:27], v[148:151], v[164:167], v[24:27]
	v_mfma_f32_16x16x32_bf16 v[20:23], v[148:151], v[168:171], v[20:23]
	s_add_u32 m0, s4, 0x5000
	s_nop 0
	global_load_lds_dwordx4 v57, s[2:3]
	v_mfma_f32_16x16x32_bf16 v[16:19], v[152:155], v[156:159], v[16:19]
	v_mfma_f32_16x16x32_bf16 v[12:15], v[152:155], v[160:163], v[12:15]
	s_add_u32 m0, s4, 0x6000
	s_nop 0
	global_load_lds_dwordx4 v58, s[2:3]
	v_mfma_f32_16x16x32_bf16 v[8:11], v[152:155], v[164:167], v[8:11]
	v_mfma_f32_16x16x32_bf16 v[4:7], v[152:155], v[168:171], v[4:7]
	s_add_u32 m0, s4, 0x7000
	s_nop 0
	global_load_lds_dwordx4 v59, s[2:3]
	s_add_u32 s0, s0, 0x80
	s_addc_u32 s1, s1, 0
	s_add_u32 s2, s2, 0x80
	s_addc_u32 s3, s3, 0
	s_waitcnt vmcnt(0) lgkmcnt(0)
	s_barrier
	ds_read_b128 v[140:143], v66 offset:0
	ds_read_b128 v[144:147], v66 offset:2048
	ds_read_b128 v[148:151], v66 offset:4096
	ds_read_b128 v[152:155], v66 offset:6144
	ds_read_b128 v[156:159], v64 offset:0
	ds_read_b128 v[160:163], v64 offset:2048
	ds_read_b128 v[164:167], v64 offset:4096
	ds_read_b128 v[168:171], v64 offset:6144
	v_mfma_f32_16x16x32_bf16 v[60:63], v[172:175], v[188:191], v[60:63]
	v_mfma_f32_16x16x32_bf16 v[68:71], v[172:175], v[192:195], v[68:71]
	v_mfma_f32_16x16x32_bf16 v[52:55], v[172:175], v[196:199], v[52:55]
	v_mfma_f32_16x16x32_bf16 v[40:43], v[172:175], v[200:203], v[40:43]
	v_mfma_f32_16x16x32_bf16 v[72:75], v[176:179], v[188:191], v[72:75]
	v_mfma_f32_16x16x32_bf16 v[48:51], v[176:179], v[192:195], v[48:51]
	v_mfma_f32_16x16x32_bf16 v[44:47], v[176:179], v[196:199], v[44:47]
	v_mfma_f32_16x16x32_bf16 v[36:39], v[176:179], v[200:203], v[36:39]
	v_mfma_f32_16x16x32_bf16 v[32:35], v[180:183], v[188:191], v[32:35]
	v_mfma_f32_16x16x32_bf16 v[28:31], v[180:183], v[192:195], v[28:31]
	v_mfma_f32_16x16x32_bf16 v[24:27], v[180:183], v[196:199], v[24:27]
	v_mfma_f32_16x16x32_bf16 v[20:23], v[180:183], v[200:203], v[20:23]
	v_mfma_f32_16x16x32_bf16 v[16:19], v[184:187], v[188:191], v[16:19]
	v_mfma_f32_16x16x32_bf16 v[12:15], v[184:187], v[192:195], v[12:15]
	v_mfma_f32_16x16x32_bf16 v[8:11], v[184:187], v[196:199], v[8:11]
	v_mfma_f32_16x16x32_bf16 v[4:7], v[184:187], v[200:203], v[4:7]
	s_waitcnt lgkmcnt(0)
	ds_read_b128 v[172:175], v67 offset:0
	ds_read_b128 v[176:179], v67 offset:2048
	ds_read_b128 v[180:183], v67 offset:4096
	ds_read_b128 v[184:187], v67 offset:6144
	ds_read_b128 v[188:191], v65 offset:0
	ds_read_b128 v[192:195], v65 offset:2048
	ds_read_b128 v[196:199], v65 offset:4096
	ds_read_b128 v[200:203], v65 offset:6144
	v_mfma_f32_16x16x32_bf16 v[60:63], v[140:143], v[156:159], v[60:63]
	v_mfma_f32_16x16x32_bf16 v[68:71], v[140:143], v[160:163], v[68:71]
	s_add_u32 m0, s4, 0x8000
	s_nop 0
	global_load_lds_dwordx4 v56, s[0:1]
	v_mfma_f32_16x16x32_bf16 v[52:55], v[140:143], v[164:167], v[52:55]
	v_mfma_f32_16x16x32_bf16 v[40:43], v[140:143], v[168:171], v[40:43]
	s_add_u32 m0, s4, 0x9000
	s_nop 0
	global_load_lds_dwordx4 v57, s[0:1]
	v_mfma_f32_16x16x32_bf16 v[72:75], v[144:147], v[156:159], v[72:75]
	v_mfma_f32_16x16x32_bf16 v[48:51], v[144:147], v[160:163], v[48:51]
	s_add_u32 m0, s4, 0xa000
	s_nop 0
	global_load_lds_dwordx4 v58, s[0:1]
	v_mfma_f32_16x16x32_bf16 v[44:47], v[144:147], v[164:167], v[44:47]
	v_mfma_f32_16x16x32_bf16 v[36:39], v[144:147], v[168:171], v[36:39]
	s_add_u32 m0, s4, 0xb000
	s_nop 0
	global_load_lds_dwordx4 v59, s[0:1]
	v_mfma_f32_16x16x32_bf16 v[32:35], v[148:151], v[156:159], v[32:35]
	v_mfma_f32_16x16x32_bf16 v[28:31], v[148:151], v[160:163], v[28:31]
	s_add_u32 m0, s4, 0xc000
	s_nop 0
	global_load_lds_dwordx4 v56, s[2:3]
	v_mfma_f32_16x16x32_bf16 v[24:27], v[148:151], v[164:167], v[24:27]
	v_mfma_f32_16x16x32_bf16 v[20:23], v[148:151], v[168:171], v[20:23]
	s_add_u32 m0, s4, 0xd000
	s_nop 0
	global_load_lds_dwordx4 v57, s[2:3]
	v_mfma_f32_16x16x32_bf16 v[16:19], v[152:155], v[156:159], v[16:19]
	v_mfma_f32_16x16x32_bf16 v[12:15], v[152:155], v[160:163], v[12:15]
	s_add_u32 m0, s4, 0xe000
	s_nop 0
	global_load_lds_dwordx4 v58, s[2:3]
	v_mfma_f32_16x16x32_bf16 v[8:11], v[152:155], v[164:167], v[8:11]
	v_mfma_f32_16x16x32_bf16 v[4:7], v[152:155], v[168:171], v[4:7]
	s_add_u32 m0, s4, 0xf000
	s_nop 0
	global_load_lds_dwordx4 v59, s[2:3]
	s_add_u32 s0, s0, 0x80
	s_addc_u32 s1, s1, 0
	s_add_u32 s2, s2, 0x80
	s_addc_u32 s3, s3, 0
	s_waitcnt vmcnt(0) lgkmcnt(0)
	s_barrier
	ds_read_b128 v[140:143], v66 offset:32768
	ds_read_b128 v[144:147], v66 offset:34816
	ds_read_b128 v[148:151], v66 offset:36864
	ds_read_b128 v[152:155], v66 offset:38912
	ds_read_b128 v[156:159], v64 offset:32768
	ds_read_b128 v[160:163], v64 offset:34816
	ds_read_b128 v[164:167], v64 offset:36864
	ds_read_b128 v[168:171], v64 offset:38912
	v_mfma_f32_16x16x32_bf16 v[60:63], v[172:175], v[188:191], v[60:63]
	v_mfma_f32_16x16x32_bf16 v[68:71], v[172:175], v[192:195], v[68:71]
	v_mfma_f32_16x16x32_bf16 v[52:55], v[172:175], v[196:199], v[52:55]
	v_mfma_f32_16x16x32_bf16 v[40:43], v[172:175], v[200:203], v[40:43]
	v_mfma_f32_16x16x32_bf16 v[72:75], v[176:179], v[188:191], v[72:75]
	v_mfma_f32_16x16x32_bf16 v[48:51], v[176:179], v[192:195], v[48:51]
	v_mfma_f32_16x16x32_bf16 v[44:47], v[176:179], v[196:199], v[44:47]
	v_mfma_f32_16x16x32_bf16 v[36:39], v[176:179], v[200:203], v[36:39]
	v_mfma_f32_16x16x32_bf16 v[32:35], v[180:183], v[188:191], v[32:35]
	v_mfma_f32_16x16x32_bf16 v[28:31], v[180:183], v[192:195], v[28:31]
	v_mfma_f32_16x16x32_bf16 v[24:27], v[180:183], v[196:199], v[24:27]
	v_mfma_f32_16x16x32_bf16 v[20:23], v[180:183], v[200:203], v[20:23]
	v_mfma_f32_16x16x32_bf16 v[16:19], v[184:187], v[188:191], v[16:19]
	v_mfma_f32_16x16x32_bf16 v[12:15], v[184:187], v[192:195], v[12:15]
	v_mfma_f32_16x16x32_bf16 v[8:11], v[184:187], v[196:199], v[8:11]
	v_mfma_f32_16x16x32_bf16 v[4:7], v[184:187], v[200:203], v[4:7]
	s_waitcnt lgkmcnt(0)
	ds_read_b128 v[172:175], v67 offset:32768
	ds_read_b128 v[176:179], v67 offset:34816
	ds_read_b128 v[180:183], v67 offset:36864
	ds_read_b128 v[184:187], v67 offset:38912
	ds_read_b128 v[188:191], v65 offset:32768
	ds_read_b128 v[192:195], v65 offset:34816
	ds_read_b128 v[196:199], v65 offset:36864
	ds_read_b128 v[200:203], v65 offset:38912
	v_mfma_f32_16x16x32_bf16 v[60:63], v[140:143], v[156:159], v[60:63]
	v_mfma_f32_16x16x32_bf16 v[68:71], v[140:143], v[160:163], v[68:71]
	v_mfma_f32_16x16x32_bf16 v[52:55], v[140:143], v[164:167], v[52:55]
	v_mfma_f32_16x16x32_bf16 v[40:43], v[140:143], v[168:171], v[40:43]
	v_mfma_f32_16x16x32_bf16 v[72:75], v[144:147], v[156:159], v[72:75]
	v_mfma_f32_16x16x32_bf16 v[48:51], v[144:147], v[160:163], v[48:51]
	v_mfma_f32_16x16x32_bf16 v[44:47], v[144:147], v[164:167], v[44:47]
	v_mfma_f32_16x16x32_bf16 v[36:39], v[144:147], v[168:171], v[36:39]
	v_mfma_f32_16x16x32_bf16 v[32:35], v[148:151], v[156:159], v[32:35]
	v_mfma_f32_16x16x32_bf16 v[28:31], v[148:151], v[160:163], v[28:31]
	v_mfma_f32_16x16x32_bf16 v[24:27], v[148:151], v[164:167], v[24:27]
	v_mfma_f32_16x16x32_bf16 v[20:23], v[148:151], v[168:171], v[20:23]
	v_mfma_f32_16x16x32_bf16 v[16:19], v[152:155], v[156:159], v[16:19]
	v_mfma_f32_16x16x32_bf16 v[12:15], v[152:155], v[160:163], v[12:15]
	v_mfma_f32_16x16x32_bf16 v[8:11], v[152:155], v[164:167], v[8:11]
	v_mfma_f32_16x16x32_bf16 v[4:7], v[152:155], v[168:171], v[4:7]
	s_waitcnt vmcnt(0) lgkmcnt(0)
	s_barrier
	v_mfma_f32_16x16x32_bf16 v[60:63], v[172:175], v[188:191], v[60:63]
	v_mfma_f32_16x16x32_bf16 v[68:71], v[172:175], v[192:195], v[68:71]
	v_mfma_f32_16x16x32_bf16 v[52:55], v[172:175], v[196:199], v[52:55]
	v_mfma_f32_16x16x32_bf16 v[40:43], v[172:175], v[200:203], v[40:43]
	v_mfma_f32_16x16x32_bf16 v[72:75], v[176:179], v[188:191], v[72:75]
	v_mfma_f32_16x16x32_bf16 v[48:51], v[176:179], v[192:195], v[48:51]
	v_mfma_f32_16x16x32_bf16 v[44:47], v[176:179], v[196:199], v[44:47]
	v_mfma_f32_16x16x32_bf16 v[36:39], v[176:179], v[200:203], v[36:39]
	v_mfma_f32_16x16x32_bf16 v[32:35], v[180:183], v[188:191], v[32:35]
	v_mfma_f32_16x16x32_bf16 v[28:31], v[180:183], v[192:195], v[28:31]
	v_mfma_f32_16x16x32_bf16 v[24:27], v[180:183], v[196:199], v[24:27]
	v_mfma_f32_16x16x32_bf16 v[20:23], v[180:183], v[200:203], v[20:23]
	v_mfma_f32_16x16x32_bf16 v[16:19], v[184:187], v[188:191], v[16:19]
	v_mfma_f32_16x16x32_bf16 v[12:15], v[184:187], v[192:195], v[12:15]
	v_mfma_f32_16x16x32_bf16 v[8:11], v[184:187], v[196:199], v[8:11]
	v_mfma_f32_16x16x32_bf16 v[4:7], v[184:187], v[200:203], v[4:7]
	s_branch .Lg1_join
.Lg1_narrow:
	s_add_u32 m0, s4, 0x0
	s_nop 0
	global_load_lds_dwordx4 v56, s[0:1]
	s_add_u32 m0, s4, 0x1000
	s_nop 0
	global_load_lds_dwordx4 v57, s[0:1]
	s_add_u32 m0, s4, 0x2000
	s_nop 0
	global_load_lds_dwordx4 v58, s[0:1]
	s_add_u32 m0, s4, 0x3000
	s_nop 0
	global_load_lds_dwordx4 v59, s[0:1]
	s_add_u32 m0, s4, 0x4000
	s_nop 0
	global_load_lds_dwordx4 v56, s[2:3]
	s_add_u32 s0, s0, 0x80
	s_addc_u32 s1, s1, 0
	s_add_u32 s2, s2, 0x80
	s_addc_u32 s3, s3, 0
	s_waitcnt vmcnt(0)
	s_barrier
	ds_read_b128 v[140:143], v66 offset:0
	ds_read_b128 v[144:147], v66 offset:2048
	ds_read_b128 v[156:159], v64 offset:0
	ds_read_b128 v[160:163], v64 offset:2048
	ds_read_b128 v[164:167], v64 offset:4096
	ds_read_b128 v[168:171], v64 offset:6144
	s_waitcnt lgkmcnt(0)
	ds_read_b128 v[172:175], v67 offset:0
	ds_read_b128 v[176:179], v67 offset:2048
	ds_read_b128 v[188:191], v65 offset:0
	ds_read_b128 v[192:195], v65 offset:2048
	ds_read_b128 v[196:199], v65 offset:4096
	ds_read_b128 v[200:203], v65 offset:6144
	v_mfma_f32_16x16x32_bf16 v[60:63], v[140:143], v[156:159], v[60:63]
	v_mfma_f32_16x16x32_bf16 v[68:71], v[140:143], v[160:163], v[68:71]
	s_add_u32 m0, s4, 0x8000
	s_nop 0
	global_load_lds_dwordx4 v56, s[0:1]
	v_mfma_f32_16x16x32_bf16 v[52:55], v[140:143], v[164:167], v[52:55]
	v_mfma_f32_16x16x32_bf16 v[40:43], v[140:143], v[168:171], v[40:43]
	s_add_u32 m0, s4, 0x9000
	s_nop 0
	global_load_lds_dwordx4 v57, s[0:1]
	v_mfma_f32_16x16x32_bf16 v[72:75], v[144:147], v[156:159], v[72:75]
	v_mfma_f32_16x16x32_bf16 v[48:51], v[144:147], v[160:163], v[48:51]
	s_add_u32 m0, s4, 0xa000
	s_nop 0
	global_load_lds_dwordx4 v58, s[0:1]
	v_mfma_f32_16x16x32_bf16 v[44:47], v[144:147], v[164:167], v[44:47]
	v_mfma_f32_16x16x32_bf16 v[36:39], v[144:147], v[168:171], v[36:39]
	s_add_u32 m0, s4, 0xb000
	s_nop 0
	global_load_lds_dwordx4 v59, s[0:1]
	s_add_u32 m0, s4, 0xc000
	s_nop 0
	global_load_lds_dwordx4 v56, s[2:3]
	s_add_u32 s0, s0, 0x80
	s_addc_u32 s1, s1, 0
	s_add_u32 s2, s2, 0x80
	s_addc_u32 s3, s3, 0
	s_waitcnt vmcnt(0) lgkmcnt(0)
	s_barrier
	ds_read_b128 v[140:143], v66 offset:32768
	ds_read_b128 v[144:147], v66 offset:34816
	ds_read_b128 v[156:159], v64 offset:32768
	ds_read_b128 v[160:163], v64 offset:34816
	ds_read_b128 v[164:167], v64 offset:36864
	ds_read_b128 v[168:171], v64 offset:38912
	v_mfma_f32_16x16x32_bf16 v[60:63], v[172:175], v[188:191], v[60:63]
	v_mfma_f32_16x16x32_bf16 v[68:71], v[172:175], v[192:195], v[68:71]
	v_mfma_f32_16x16x32_bf16 v[52:55], v[172:175], v[196:199], v[52:55]
	v_mfma_f32_16x16x32_bf16 v[40:43], v[172:175], v[200:203], v[40:43]
	v_mfma_f32_16x16x32_bf16 v[72:75], v[176:179], v[188:191], v[72:75]
	v_mfma_f32_16x16x32_bf16 v[48:51], v[176:179], v[192:195], v[48:51]
	v_mfma_f32_16x16x32_bf16 v[44:47], v[176:179], v[196:199], v[44:47]
	v_mfma_f32_16x16x32_bf16 v[36:39], v[176:179], v[200:203], v[36:39]
	s_waitcnt lgkmcnt(0)
	ds_read_b128 v[172:175], v67 offset:32768
	ds_read_b128 v[176:179], v67 offset:34816
	ds_read_b128 v[188:191], v65 offset:32768
	ds_read_b128 v[192:195], v65 offset:34816
	ds_read_b128 v[196:199], v65 offset:36864
	ds_read_b128 v[200:203], v65 offset:38912
	v_mfma_f32_16x16x32_bf16 v[60:63], v[140:143], v[156:159], v[60:63]
	v_mfma_f32_16x16x32_bf16 v[68:71], v[140:143], v[160:163], v[68:71]
	s_add_u32 m0, s4, 0x0
	s_nop 0
	global_load_lds_dwordx4 v56, s[0:1]
	v_mfma_f32_16x16x32_bf16 v[52:55], v[140:143], v[164:167], v[52:55]
	v_mfma_f32_16x16x32_bf16 v[40:43], v[140:143], v[168:171], v[40:43]
	s_add_u32 m0, s4, 0x1000
	s_nop 0
	global_load_lds_dwordx4 v57, s[0:1]
	v_mfma_f32_16x16x32_bf16 v[72:75], v[144:147], v[156:159], v[72:75]
	v_mfma_f32_16x16x32_bf16 v[48:51], v[144:147], v[160:163], v[48:51]
	s_add_u32 m0, s4, 0x2000
	s_nop 0
	global_load_lds_dwordx4 v58, s[0:1]
	v_mfma_f32_16x16x32_bf16 v[44:47], v[144:147], v[164:167], v[44:47]
	v_mfma_f32_16x16x32_bf16 v[36:39], v[144:147], v[168:171], v[36:39]
	s_add_u32 m0, s4, 0x3000
	s_nop 0
	global_load_lds_dwordx4 v59, s[0:1]
	s_add_u32 m0, s4, 0x4000
	s_nop 0
	global_load_lds_dwordx4 v56, s[2:3]
	s_add_u32 s0, s0, 0x80
	s_addc_u32 s1, s1, 0
	s_add_u32 s2, s2, 0x80
	s_addc_u32 s3, s3, 0
	s_waitcnt vmcnt(0) lgkmcnt(0)
	s_barrier
	ds_read_b128 v[140:143], v66 offset:0
	ds_read_b128 v[144:147], v66 offset:2048
	ds_read_b128 v[156:159], v64 offset:0
	ds_read_b128 v[160:163], v64 offset:2048
	ds_read_b128 v[164:167], v64 offset:4096
	ds_read_b128 v[168:171], v64 offset:6144
	v_mfma_f32_16x16x32_bf16 v[60:63], v[172:175], v[188:191], v[60:63]
	v_mfma_f32_16x16x32_bf16 v[68:71], v[172:175], v[192:195], v[68:71]
	v_mfma_f32_16x16x32_bf16 v[52:55], v[172:175], v[196:199], v[52:55]
	v_mfma_f32_16x16x32_bf16 v[40:43], v[172:175], v[200:203], v[40:43]
	v_mfma_f32_16x16x32_bf16 v[72:75], v[176:179], v[188:191], v[72:75]
	v_mfma_f32_16x16x32_bf16 v[48:51], v[176:179], v[192:195], v[48:51]
	v_mfma_f32_16x16x32_bf16 v[44:47], v[176:179], v[196:199], v[44:47]
	v_mfma_f32_16x16x32_bf16 v[36:39], v[176:179], v[200:203], v[36:39]
	s_waitcnt lgkmcnt(0)
	ds_read_b128 v[172:175], v67 offset:0
	ds_read_b128 v[176:179], v67 offset:2048
	ds_read_b128 v[188:191], v65 offset:0
	ds_read_b128 v[192:195], v65 offset:2048
	ds_read_b128 v[196:199], v65 offset:4096
	ds_read_b128 v[200:203], v65 offset:6144
	v_mfma_f32_16x16x32_bf16 v[60:63], v[140:143], v[156:159], v[60:63]
	v_mfma_f32_16x16x32_bf16 v[68:71], v[140:143], v[160:163], v[68:71]
	s_add_u32 m0, s4, 0x8000
	s_nop 0
	global_load_lds_dwordx4 v56, s[0:1]
	v_mfma_f32_16x16x32_bf16 v[52:55], v[140:143], v[164:167], v[52:55]
	v_mfma_f32_16x16x32_bf16 v[40:43], v[140:143], v[168:171], v[40:43]
	s_add_u32 m0, s4, 0x9000
	s_nop 0
	global_load_lds_dwordx4 v57, s[0:1]
	v_mfma_f32_16x16x32_bf16 v[72:75], v[144:147], v[156:159], v[72:75]
	v_mfma_f32_16x16x32_bf16 v[48:51], v[144:147], v[160:163], v[48:51]
	s_add_u32 m0, s4, 0xa000
	s_nop 0
	global_load_lds_dwordx4 v58, s[0:1]
	v_mfma_f32_16x16x32_bf16 v[44:47], v[144:147], v[164:167], v[44:47]
	v_mfma_f32_16x16x32_bf16 v[36:39], v[144:147], v[168:171], v[36:39]
	s_add_u32 m0, s4, 0xb000
	s_nop 0
	global_load_lds_dwordx4 v59, s[0:1]
	s_add_u32 m0, s4, 0xc000
	s_nop 0
	global_load_lds_dwordx4 v56, s[2:3]
	s_add_u32 s0, s0, 0x80
	s_addc_u32 s1, s1, 0
	s_add_u32 s2, s2, 0x80
	s_addc_u32 s3, s3, 0
	s_waitcnt vmcnt(0) lgkmcnt(0)
	s_barrier
	ds_read_b128 v[140:143], v66 offset:32768
	ds_read_b128 v[144:147], v66 offset:34816
	ds_read_b128 v[156:159], v64 offset:32768
	ds_read_b128 v[160:163], v64 offset:34816
	ds_read_b128 v[164:167], v64 offset:36864
	ds_read_b128 v[168:171], v64 offset:38912
	v_mfma_f32_16x16x32_bf16 v[60:63], v[172:175], v[188:191], v[60:63]
	v_mfma_f32_16x16x32_bf16 v[68:71], v[172:175], v[192:195], v[68:71]
	v_mfma_f32_16x16x32_bf16 v[52:55], v[172:175], v[196:199], v[52:55]
	v_mfma_f32_16x16x32_bf16 v[40:43], v[172:175], v[200:203], v[40:43]
	v_mfma_f32_16x16x32_bf16 v[72:75], v[176:179], v[188:191], v[72:75]
	v_mfma_f32_16x16x32_bf16 v[48:51], v[176:179], v[192:195], v[48:51]
	v_mfma_f32_16x16x32_bf16 v[44:47], v[176:179], v[196:199], v[44:47]
	v_mfma_f32_16x16x32_bf16 v[36:39], v[176:179], v[200:203], v[36:39]
	s_waitcnt lgkmcnt(0)
	ds_read_b128 v[172:175], v67 offset:32768
	ds_read_b128 v[176:179], v67 offset:34816
	ds_read_b128 v[188:191], v65 offset:32768
	ds_read_b128 v[192:195], v65 offset:34816
	ds_read_b128 v[196:199], v65 offset:36864
	ds_read_b128 v[200:203], v65 offset:38912
	v_mfma_f32_16x16x32_bf16 v[60:63], v[140:143], v[156:159], v[60:63]
	v_mfma_f32_16x16x32_bf16 v[68:71], v[140:143], v[160:163], v[68:71]
	s_add_u32 m0, s4, 0x0
	s_nop 0
	global_load_lds_dwordx4 v56, s[0:1]
	v_mfma_f32_16x16x32_bf16 v[52:55], v[140:143], v[164:167], v[52:55]
	v_mfma_f32_16x16x32_bf16 v[40:43], v[140:143], v[168:171], v[40:43]
	s_add_u32 m0, s4, 0x1000
	s_nop 0
	global_load_lds_dwordx4 v57, s[0:1]
	v_mfma_f32_16x16x32_bf16 v[72:75], v[144:147], v[156:159], v[72:75]
	v_mfma_f32_16x16x32_bf16 v[48:51], v[144:147], v[160:163], v[48:51]
	s_add_u32 m0, s4, 0x2000
	s_nop 0
	global_load_lds_dwordx4 v58, s[0:1]
	v_mfma_f32_16x16x32_bf16 v[44:47], v[144:147], v[164:167], v[44:47]
	v_mfma_f32_16x16x32_bf16 v[36:39], v[144:147], v[168:171], v[36:39]
	s_add_u32 m0, s4, 0x3000
	s_nop 0
	global_load_lds_dwordx4 v59, s[0:1]
	s_add_u32 m0, s4, 0x4000
	s_nop 0
	global_load_lds_dwordx4 v56, s[2:3]
	s_add_u32 s0, s0, 0x80
	s_addc_u32 s1, s1, 0
	s_add_u32 s2, s2, 0x80
	s_addc_u32 s3, s3, 0
	s_waitcnt vmcnt(0) lgkmcnt(0)
	s_barrier
	ds_read_b128 v[140:143], v66 offset:0
	ds_read_b128 v[144:147], v66 offset:2048
	ds_read_b128 v[156:159], v64 offset:0
	ds_read_b128 v[160:163], v64 offset:2048
	ds_read_b128 v[164:167], v64 offset:4096
	ds_read_b128 v[168:171], v64 offset:6144
	v_mfma_f32_16x16x32_bf16 v[60:63], v[172:175], v[188:191], v[60:63]
	v_mfma_f32_16x16x32_bf16 v[68:71], v[172:175], v[192:195], v[68:71]
	v_mfma_f32_16x16x32_bf16 v[52:55], v[172:175], v[196:199], v[52:55]
	v_mfma_f32_16x16x32_bf16 v[40:43], v[172:175], v[200:203], v[40:43]
	v_mfma_f32_16x16x32_bf16 v[72:75], v[176:179], v[188:191], v[72:75]
	v_mfma_f32_16x16x32_bf16 v[48:51], v[176:179], v[192:195], v[48:51]
	v_mfma_f32_16x16x32_bf16 v[44:47], v[176:179], v[196:199], v[44:47]
	v_mfma_f32_16x16x32_bf16 v[36:39], v[176:179], v[200:203], v[36:39]
	s_waitcnt lgkmcnt(0)
	ds_read_b128 v[172:175], v67 offset:0
	ds_read_b128 v[176:179], v67 offset:2048
	ds_read_b128 v[188:191], v65 offset:0
	ds_read_b128 v[192:195], v65 offset:2048
	ds_read_b128 v[196:199], v65 offset:4096
	ds_read_b128 v[200:203], v65 offset:6144
	v_mfma_f32_16x16x32_bf16 v[60:63], v[140:143], v[156:159], v[60:63]
	v_mfma_f32_16x16x32_bf16 v[68:71], v[140:143], v[160:163], v[68:71]
	s_add_u32 m0, s4, 0x8000
	s_nop 0
	global_load_lds_dwordx4 v56, s[0:1]
	v_mfma_f32_16x16x32_bf16 v[52:55], v[140:143], v[164:167], v[52:55]
	v_mfma_f32_16x16x32_bf16 v[40:43], v[140:143], v[168:171], v[40:43]
	s_add_u32 m0, s4, 0x9000
	s_nop 0
	global_load_lds_dwordx4 v57, s[0:1]
	v_mfma_f32_16x16x32_bf16 v[72:75], v[144:147], v[156:159], v[72:75]
	v_mfma_f32_16x16x32_bf16 v[48:51], v[144:147], v[160:163], v[48:51]
	s_add_u32 m0, s4, 0xa000
	s_nop 0
	global_load_lds_dwordx4 v58, s[0:1]
	v_mfma_f32_16x16x32_bf16 v[44:47], v[144:147], v[164:167], v[44:47]
	v_mfma_f32_16x16x32_bf16 v[36:39], v[144:147], v[168:171], v[36:39]
	s_add_u32 m0, s4, 0xb000
	s_nop 0
	global_load_lds_dwordx4 v59, s[0:1]
	s_add_u32 m0, s4, 0xc000
	s_nop 0
	global_load_lds_dwordx4 v56, s[2:3]
	s_add_u32 s0, s0, 0x80
	s_addc_u32 s1, s1, 0
	s_add_u32 s2, s2, 0x80
	s_addc_u32 s3, s3, 0
	s_waitcnt vmcnt(0) lgkmcnt(0)
	s_barrier
	ds_read_b128 v[140:143], v66 offset:32768
	ds_read_b128 v[144:147], v66 offset:34816
	ds_read_b128 v[156:159], v64 offset:32768
	ds_read_b128 v[160:163], v64 offset:34816
	ds_read_b128 v[164:167], v64 offset:36864
	ds_read_b128 v[168:171], v64 offset:38912
	v_mfma_f32_16x16x32_bf16 v[60:63], v[172:175], v[188:191], v[60:63]
	v_mfma_f32_16x16x32_bf16 v[68:71], v[172:175], v[192:195], v[68:71]
	v_mfma_f32_16x16x32_bf16 v[52:55], v[172:175], v[196:199], v[52:55]
	v_mfma_f32_16x16x32_bf16 v[40:43], v[172:175], v[200:203], v[40:43]
	v_mfma_f32_16x16x32_bf16 v[72:75], v[176:179], v[188:191], v[72:75]
	v_mfma_f32_16x16x32_bf16 v[48:51], v[176:179], v[192:195], v[48:51]
	v_mfma_f32_16x16x32_bf16 v[44:47], v[176:179], v[196:199], v[44:47]
	v_mfma_f32_16x16x32_bf16 v[36:39], v[176:179], v[200:203], v[36:39]
	s_waitcnt lgkmcnt(0)
	ds_read_b128 v[172:175], v67 offset:32768
	ds_read_b128 v[176:179], v67 offset:34816
	ds_read_b128 v[188:191], v65 offset:32768
	ds_read_b128 v[192:195], v65 offset:34816
	ds_read_b128 v[196:199], v65 offset:36864
	ds_read_b128 v[200:203], v65 offset:38912
	v_mfma_f32_16x16x32_bf16 v[60:63], v[140:143], v[156:159], v[60:63]
	v_mfma_f32_16x16x32_bf16 v[68:71], v[140:143], v[160:163], v[68:71]
	s_add_u32 m0, s4, 0x0
	s_nop 0
	global_load_lds_dwordx4 v56, s[0:1]
	v_mfma_f32_16x16x32_bf16 v[52:55], v[140:143], v[164:167], v[52:55]
	v_mfma_f32_16x16x32_bf16 v[40:43], v[140:143], v[168:171], v[40:43]
	s_add_u32 m0, s4, 0x1000
	s_nop 0
	global_load_lds_dwordx4 v57, s[0:1]
	v_mfma_f32_16x16x32_bf16 v[72:75], v[144:147], v[156:159], v[72:75]
	v_mfma_f32_16x16x32_bf16 v[48:51], v[144:147], v[160:163], v[48:51]
	s_add_u32 m0, s4, 0x2000
	s_nop 0
	global_load_lds_dwordx4 v58, s[0:1]
	v_mfma_f32_16x16x32_bf16 v[44:47], v[144:147], v[164:167], v[44:47]
	v_mfma_f32_16x16x32_bf16 v[36:39], v[144:147], v[168:171], v[36:39]
	s_add_u32 m0, s4, 0x3000
	s_nop 0
	global_load_lds_dwordx4 v59, s[0:1]
	s_add_u32 m0, s4, 0x4000
	s_nop 0
	global_load_lds_dwordx4 v56, s[2:3]
	s_add_u32 s0, s0, 0x80
	s_addc_u32 s1, s1, 0
	s_add_u32 s2, s2, 0x80
	s_addc_u32 s3, s3, 0
	s_waitcnt vmcnt(0) lgkmcnt(0)
	s_barrier
	ds_read_b128 v[140:143], v66 offset:0
	ds_read_b128 v[144:147], v66 offset:2048
	ds_read_b128 v[156:159], v64 offset:0
	ds_read_b128 v[160:163], v64 offset:2048
	ds_read_b128 v[164:167], v64 offset:4096
	ds_read_b128 v[168:171], v64 offset:6144
	v_mfma_f32_16x16x32_bf16 v[60:63], v[172:175], v[188:191], v[60:63]
	v_mfma_f32_16x16x32_bf16 v[68:71], v[172:175], v[192:195], v[68:71]
	v_mfma_f32_16x16x32_bf16 v[52:55], v[172:175], v[196:199], v[52:55]
	v_mfma_f32_16x16x32_bf16 v[40:43], v[172:175], v[200:203], v[40:43]
	v_mfma_f32_16x16x32_bf16 v[72:75], v[176:179], v[188:191], v[72:75]
	v_mfma_f32_16x16x32_bf16 v[48:51], v[176:179], v[192:195], v[48:51]
	v_mfma_f32_16x16x32_bf16 v[44:47], v[176:179], v[196:199], v[44:47]
	v_mfma_f32_16x16x32_bf16 v[36:39], v[176:179], v[200:203], v[36:39]
	s_waitcnt lgkmcnt(0)
	ds_read_b128 v[172:175], v67 offset:0
	ds_read_b128 v[176:179], v67 offset:2048
	ds_read_b128 v[188:191], v65 offset:0
	ds_read_b128 v[192:195], v65 offset:2048
	ds_read_b128 v[196:199], v65 offset:4096
	ds_read_b128 v[200:203], v65 offset:6144
	v_mfma_f32_16x16x32_bf16 v[60:63], v[140:143], v[156:159], v[60:63]
	v_mfma_f32_16x16x32_bf16 v[68:71], v[140:143], v[160:163], v[68:71]
	s_add_u32 m0, s4, 0x8000
	s_nop 0
	global_load_lds_dwordx4 v56, s[0:1]
	v_mfma_f32_16x16x32_bf16 v[52:55], v[140:143], v[164:167], v[52:55]
	v_mfma_f32_16x16x32_bf16 v[40:43], v[140:143], v[168:171], v[40:43]
	s_add_u32 m0, s4, 0x9000
	s_nop 0
	global_load_lds_dwordx4 v57, s[0:1]
	v_mfma_f32_16x16x32_bf16 v[72:75], v[144:147], v[156:159], v[72:75]
	v_mfma_f32_16x16x32_bf16 v[48:51], v[144:147], v[160:163], v[48:51]
	s_add_u32 m0, s4, 0xa000
	s_nop 0
	global_load_lds_dwordx4 v58, s[0:1]
	v_mfma_f32_16x16x32_bf16 v[44:47], v[144:147], v[164:167], v[44:47]
	v_mfma_f32_16x16x32_bf16 v[36:39], v[144:147], v[168:171], v[36:39]
	s_add_u32 m0, s4, 0xb000
	s_nop 0
	global_load_lds_dwordx4 v59, s[0:1]
	s_add_u32 m0, s4, 0xc000
	s_nop 0
	global_load_lds_dwordx4 v56, s[2:3]
	s_add_u32 s0, s0, 0x80
	s_addc_u32 s1, s1, 0
	s_add_u32 s2, s2, 0x80
	s_addc_u32 s3, s3, 0
	s_waitcnt vmcnt(0) lgkmcnt(0)
	s_barrier
	ds_read_b128 v[140:143], v66 offset:32768
	ds_read_b128 v[144:147], v66 offset:34816
	ds_read_b128 v[156:159], v64 offset:32768
	ds_read_b128 v[160:163], v64 offset:34816
	ds_read_b128 v[164:167], v64 offset:36864
	ds_read_b128 v[168:171], v64 offset:38912
	v_mfma_f32_16x16x32_bf16 v[60:63], v[172:175], v[188:191], v[60:63]
	v_mfma_f32_16x16x32_bf16 v[68:71], v[172:175], v[192:195], v[68:71]
	v_mfma_f32_16x16x32_bf16 v[52:55], v[172:175], v[196:199], v[52:55]
	v_mfma_f32_16x16x32_bf16 v[40:43], v[172:175], v[200:203], v[40:43]
	v_mfma_f32_16x16x32_bf16 v[72:75], v[176:179], v[188:191], v[72:75]
	v_mfma_f32_16x16x32_bf16 v[48:51], v[176:179], v[192:195], v[48:51]
	v_mfma_f32_16x16x32_bf16 v[44:47], v[176:179], v[196:199], v[44:47]
	v_mfma_f32_16x16x32_bf16 v[36:39], v[176:179], v[200:203], v[36:39]
	s_waitcnt lgkmcnt(0)
	ds_read_b128 v[172:175], v67 offset:32768
	ds_read_b128 v[176:179], v67 offset:34816
	ds_read_b128 v[188:191], v65 offset:32768
	ds_read_b128 v[192:195], v65 offset:34816
	ds_read_b128 v[196:199], v65 offset:36864
	ds_read_b128 v[200:203], v65 offset:38912
	v_mfma_f32_16x16x32_bf16 v[60:63], v[140:143], v[156:159], v[60:63]
	v_mfma_f32_16x16x32_bf16 v[68:71], v[140:143], v[160:163], v[68:71]
	s_add_u32 m0, s4, 0x0
	s_nop 0
	global_load_lds_dwordx4 v56, s[0:1]
	v_mfma_f32_16x16x32_bf16 v[52:55], v[140:143], v[164:167], v[52:55]
	v_mfma_f32_16x16x32_bf16 v[40:43], v[140:143], v[168:171], v[40:43]
	s_add_u32 m0, s4, 0x1000
	s_nop 0
	global_load_lds_dwordx4 v57, s[0:1]
	v_mfma_f32_16x16x32_bf16 v[72:75], v[144:147], v[156:159], v[72:75]
	v_mfma_f32_16x16x32_bf16 v[48:51], v[144:147], v[160:163], v[48:51]
	s_add_u32 m0, s4, 0x2000
	s_nop 0
	global_load_lds_dwordx4 v58, s[0:1]
	v_mfma_f32_16x16x32_bf16 v[44:47], v[144:147], v[164:167], v[44:47]
	v_mfma_f32_16x16x32_bf16 v[36:39], v[144:147], v[168:171], v[36:39]
	s_add_u32 m0, s4, 0x3000
	s_nop 0
	global_load_lds_dwordx4 v59, s[0:1]
	s_add_u32 m0, s4, 0x4000
	s_nop 0
	global_load_lds_dwordx4 v56, s[2:3]
	s_add_u32 s0, s0, 0x80
	s_addc_u32 s1, s1, 0
	s_add_u32 s2, s2, 0x80
	s_addc_u32 s3, s3, 0
	s_waitcnt vmcnt(0) lgkmcnt(0)
	s_barrier
	ds_read_b128 v[140:143], v66 offset:0
	ds_read_b128 v[144:147], v66 offset:2048
	ds_read_b128 v[156:159], v64 offset:0
	ds_read_b128 v[160:163], v64 offset:2048
	ds_read_b128 v[164:167], v64 offset:4096
	ds_read_b128 v[168:171], v64 offset:6144
	v_mfma_f32_16x16x32_bf16 v[60:63], v[172:175], v[188:191], v[60:63]
	v_mfma_f32_16x16x32_bf16 v[68:71], v[172:175], v[192:195], v[68:71]
	v_mfma_f32_16x16x32_bf16 v[52:55], v[172:175], v[196:199], v[52:55]
	v_mfma_f32_16x16x32_bf16 v[40:43], v[172:175], v[200:203], v[40:43]
	v_mfma_f32_16x16x32_bf16 v[72:75], v[176:179], v[188:191], v[72:75]
	v_mfma_f32_16x16x32_bf16 v[48:51], v[176:179], v[192:195], v[48:51]
	v_mfma_f32_16x16x32_bf16 v[44:47], v[176:179], v[196:199], v[44:47]
	v_mfma_f32_16x16x32_bf16 v[36:39], v[176:179], v[200:203], v[36:39]
	s_waitcnt lgkmcnt(0)
	ds_read_b128 v[172:175], v67 offset:0
	ds_read_b128 v[176:179], v67 offset:2048
	ds_read_b128 v[188:191], v65 offset:0
	ds_read_b128 v[192:195], v65 offset:2048
	ds_read_b128 v[196:199], v65 offset:4096
	ds_read_b128 v[200:203], v65 offset:6144
	v_mfma_f32_16x16x32_bf16 v[60:63], v[140:143], v[156:159], v[60:63]
	v_mfma_f32_16x16x32_bf16 v[68:71], v[140:143], v[160:163], v[68:71]
	s_add_u32 m0, s4, 0x8000
	s_nop 0
	global_load_lds_dwordx4 v56, s[0:1]
	v_mfma_f32_16x16x32_bf16 v[52:55], v[140:143], v[164:167], v[52:55]
	v_mfma_f32_16x16x32_bf16 v[40:43], v[140:143], v[168:171], v[40:43]
	s_add_u32 m0, s4, 0x9000
	s_nop 0
	global_load_lds_dwordx4 v57, s[0:1]
	v_mfma_f32_16x16x32_bf16 v[72:75], v[144:147], v[156:159], v[72:75]
	v_mfma_f32_16x16x32_bf16 v[48:51], v[144:147], v[160:163], v[48:51]
	s_add_u32 m0, s4, 0xa000
	s_nop 0
	global_load_lds_dwordx4 v58, s[0:1]
	v_mfma_f32_16x16x32_bf16 v[44:47], v[144:147], v[164:167], v[44:47]
	v_mfma_f32_16x16x32_bf16 v[36:39], v[144:147], v[168:171], v[36:39]
	s_add_u32 m0, s4, 0xb000
	s_nop 0
	global_load_lds_dwordx4 v59, s[0:1]
	s_add_u32 m0, s4, 0xc000
	s_nop 0
	global_load_lds_dwordx4 v56, s[2:3]
	s_add_u32 s0, s0, 0x80
	s_addc_u32 s1, s1, 0
	s_add_u32 s2, s2, 0x80
	s_addc_u32 s3, s3, 0
	s_waitcnt vmcnt(0) lgkmcnt(0)
	s_barrier
	ds_read_b128 v[140:143], v66 offset:32768
	ds_read_b128 v[144:147], v66 offset:34816
	ds_read_b128 v[156:159], v64 offset:32768
	ds_read_b128 v[160:163], v64 offset:34816
	ds_read_b128 v[164:167], v64 offset:36864
	ds_read_b128 v[168:171], v64 offset:38912
	v_mfma_f32_16x16x32_bf16 v[60:63], v[172:175], v[188:191], v[60:63]
	v_mfma_f32_16x16x32_bf16 v[68:71], v[172:175], v[192:195], v[68:71]
	v_mfma_f32_16x16x32_bf16 v[52:55], v[172:175], v[196:199], v[52:55]
	v_mfma_f32_16x16x32_bf16 v[40:43], v[172:175], v[200:203], v[40:43]
	v_mfma_f32_16x16x32_bf16 v[72:75], v[176:179], v[188:191], v[72:75]
	v_mfma_f32_16x16x32_bf16 v[48:51], v[176:179], v[192:195], v[48:51]
	v_mfma_f32_16x16x32_bf16 v[44:47], v[176:179], v[196:199], v[44:47]
	v_mfma_f32_16x16x32_bf16 v[36:39], v[176:179], v[200:203], v[36:39]
	s_waitcnt lgkmcnt(0)
	ds_read_b128 v[172:175], v67 offset:32768
	ds_read_b128 v[176:179], v67 offset:34816
	ds_read_b128 v[188:191], v65 offset:32768
	ds_read_b128 v[192:195], v65 offset:34816
	ds_read_b128 v[196:199], v65 offset:36864
	ds_read_b128 v[200:203], v65 offset:38912
	v_mfma_f32_16x16x32_bf16 v[60:63], v[140:143], v[156:159], v[60:63]
	v_mfma_f32_16x16x32_bf16 v[68:71], v[140:143], v[160:163], v[68:71]
	s_add_u32 m0, s4, 0x0
	s_nop 0
	global_load_lds_dwordx4 v56, s[0:1]
	v_mfma_f32_16x16x32_bf16 v[52:55], v[140:143], v[164:167], v[52:55]
	v_mfma_f32_16x16x32_bf16 v[40:43], v[140:143], v[168:171], v[40:43]
	s_add_u32 m0, s4, 0x1000
	s_nop 0
	global_load_lds_dwordx4 v57, s[0:1]
	v_mfma_f32_16x16x32_bf16 v[72:75], v[144:147], v[156:159], v[72:75]
	v_mfma_f32_16x16x32_bf16 v[48:51], v[144:147], v[160:163], v[48:51]
	s_add_u32 m0, s4, 0x2000
	s_nop 0
	global_load_lds_dwordx4 v58, s[0:1]
	v_mfma_f32_16x16x32_bf16 v[44:47], v[144:147], v[164:167], v[44:47]
	v_mfma_f32_16x16x32_bf16 v[36:39], v[144:147], v[168:171], v[36:39]
	s_add_u32 m0, s4, 0x3000
	s_nop 0
	global_load_lds_dwordx4 v59, s[0:1]
	s_add_u32 m0, s4, 0x4000
	s_nop 0
	global_load_lds_dwordx4 v56, s[2:3]
	s_add_u32 s0, s0, 0x80
	s_addc_u32 s1, s1, 0
	s_add_u32 s2, s2, 0x80
	s_addc_u32 s3, s3, 0
	s_waitcnt vmcnt(0) lgkmcnt(0)
	s_barrier
	ds_read_b128 v[140:143], v66 offset:0
	ds_read_b128 v[144:147], v66 offset:2048
	ds_read_b128 v[156:159], v64 offset:0
	ds_read_b128 v[160:163], v64 offset:2048
	ds_read_b128 v[164:167], v64 offset:4096
	ds_read_b128 v[168:171], v64 offset:6144
	v_mfma_f32_16x16x32_bf16 v[60:63], v[172:175], v[188:191], v[60:63]
	v_mfma_f32_16x16x32_bf16 v[68:71], v[172:175], v[192:195], v[68:71]
	v_mfma_f32_16x16x32_bf16 v[52:55], v[172:175], v[196:199], v[52:55]
	v_mfma_f32_16x16x32_bf16 v[40:43], v[172:175], v[200:203], v[40:43]
	v_mfma_f32_16x16x32_bf16 v[72:75], v[176:179], v[188:191], v[72:75]
	v_mfma_f32_16x16x32_bf16 v[48:51], v[176:179], v[192:195], v[48:51]
	v_mfma_f32_16x16x32_bf16 v[44:47], v[176:179], v[196:199], v[44:47]
	v_mfma_f32_16x16x32_bf16 v[36:39], v[176:179], v[200:203], v[36:39]
	s_waitcnt lgkmcnt(0)
	ds_read_b128 v[172:175], v67 offset:0
	ds_read_b128 v[176:179], v67 offset:2048
	ds_read_b128 v[188:191], v65 offset:0
	ds_read_b128 v[192:195], v65 offset:2048
	ds_read_b128 v[196:199], v65 offset:4096
	ds_read_b128 v[200:203], v65 offset:6144
	v_mfma_f32_16x16x32_bf16 v[60:63], v[140:143], v[156:159], v[60:63]
	v_mfma_f32_16x16x32_bf16 v[68:71], v[140:143], v[160:163], v[68:71]
	s_add_u32 m0, s4, 0x8000
	s_nop 0
	global_load_lds_dwordx4 v56, s[0:1]
	v_mfma_f32_16x16x32_bf16 v[52:55], v[140:143], v[164:167], v[52:55]
	v_mfma_f32_16x16x32_bf16 v[40:43], v[140:143], v[168:171], v[40:43]
	s_add_u32 m0, s4, 0x9000
	s_nop 0
	global_load_lds_dwordx4 v57, s[0:1]
	v_mfma_f32_16x16x32_bf16 v[72:75], v[144:147], v[156:159], v[72:75]
	v_mfma_f32_16x16x32_bf16 v[48:51], v[144:147], v[160:163], v[48:51]
	s_add_u32 m0, s4, 0xa000
	s_nop 0
	global_load_lds_dwordx4 v58, s[0:1]
	v_mfma_f32_16x16x32_bf16 v[44:47], v[144:147], v[164:167], v[44:47]
	v_mfma_f32_16x16x32_bf16 v[36:39], v[144:147], v[168:171], v[36:39]
	s_add_u32 m0, s4, 0xb000
	s_nop 0
	global_load_lds_dwordx4 v59, s[0:1]
	s_add_u32 m0, s4, 0xc000
	s_nop 0
	global_load_lds_dwordx4 v56, s[2:3]
	s_add_u32 s0, s0, 0x80
	s_addc_u32 s1, s1, 0
	s_add_u32 s2, s2, 0x80
	s_addc_u32 s3, s3, 0
	s_waitcnt vmcnt(0) lgkmcnt(0)
	s_barrier
	ds_read_b128 v[140:143], v66 offset:32768
	ds_read_b128 v[144:147], v66 offset:34816
	ds_read_b128 v[156:159], v64 offset:32768
	ds_read_b128 v[160:163], v64 offset:34816
	ds_read_b128 v[164:167], v64 offset:36864
	ds_read_b128 v[168:171], v64 offset:38912
	v_mfma_f32_16x16x32_bf16 v[60:63], v[172:175], v[188:191], v[60:63]
	v_mfma_f32_16x16x32_bf16 v[68:71], v[172:175], v[192:195], v[68:71]
	v_mfma_f32_16x16x32_bf16 v[52:55], v[172:175], v[196:199], v[52:55]
	v_mfma_f32_16x16x32_bf16 v[40:43], v[172:175], v[200:203], v[40:43]
	v_mfma_f32_16x16x32_bf16 v[72:75], v[176:179], v[188:191], v[72:75]
	v_mfma_f32_16x16x32_bf16 v[48:51], v[176:179], v[192:195], v[48:51]
	v_mfma_f32_16x16x32_bf16 v[44:47], v[176:179], v[196:199], v[44:47]
	v_mfma_f32_16x16x32_bf16 v[36:39], v[176:179], v[200:203], v[36:39]
	s_waitcnt lgkmcnt(0)
	ds_read_b128 v[172:175], v67 offset:32768
	ds_read_b128 v[176:179], v67 offset:34816
	ds_read_b128 v[188:191], v65 offset:32768
	ds_read_b128 v[192:195], v65 offset:34816
	ds_read_b128 v[196:199], v65 offset:36864
	ds_read_b128 v[200:203], v65 offset:38912
	v_mfma_f32_16x16x32_bf16 v[60:63], v[140:143], v[156:159], v[60:63]
	v_mfma_f32_16x16x32_bf16 v[68:71], v[140:143], v[160:163], v[68:71]
	s_add_u32 m0, s4, 0x0
	s_nop 0
	global_load_lds_dwordx4 v56, s[0:1]
	v_mfma_f32_16x16x32_bf16 v[52:55], v[140:143], v[164:167], v[52:55]
	v_mfma_f32_16x16x32_bf16 v[40:43], v[140:143], v[168:171], v[40:43]
	s_add_u32 m0, s4, 0x1000
	s_nop 0
	global_load_lds_dwordx4 v57, s[0:1]
	v_mfma_f32_16x16x32_bf16 v[72:75], v[144:147], v[156:159], v[72:75]
	v_mfma_f32_16x16x32_bf16 v[48:51], v[144:147], v[160:163], v[48:51]
	s_add_u32 m0, s4, 0x2000
	s_nop 0
	global_load_lds_dwordx4 v58, s[0:1]
	v_mfma_f32_16x16x32_bf16 v[44:47], v[144:147], v[164:167], v[44:47]
	v_mfma_f32_16x16x32_bf16 v[36:39], v[144:147], v[168:171], v[36:39]
	s_add_u32 m0, s4, 0x3000
	s_nop 0
	global_load_lds_dwordx4 v59, s[0:1]
	s_add_u32 m0, s4, 0x4000
	s_nop 0
	global_load_lds_dwordx4 v56, s[2:3]
	s_add_u32 s0, s0, 0x80
	s_addc_u32 s1, s1, 0
	s_add_u32 s2, s2, 0x80
	s_addc_u32 s3, s3, 0
	s_waitcnt vmcnt(0) lgkmcnt(0)
	s_barrier
	ds_read_b128 v[140:143], v66 offset:0
	ds_read_b128 v[144:147], v66 offset:2048
	ds_read_b128 v[156:159], v64 offset:0
	ds_read_b128 v[160:163], v64 offset:2048
	ds_read_b128 v[164:167], v64 offset:4096
	ds_read_b128 v[168:171], v64 offset:6144
	v_mfma_f32_16x16x32_bf16 v[60:63], v[172:175], v[188:191], v[60:63]
	v_mfma_f32_16x16x32_bf16 v[68:71], v[172:175], v[192:195], v[68:71]
	v_mfma_f32_16x16x32_bf16 v[52:55], v[172:175], v[196:199], v[52:55]
	v_mfma_f32_16x16x32_bf16 v[40:43], v[172:175], v[200:203], v[40:43]
	v_mfma_f32_16x16x32_bf16 v[72:75], v[176:179], v[188:191], v[72:75]
	v_mfma_f32_16x16x32_bf16 v[48:51], v[176:179], v[192:195], v[48:51]
	v_mfma_f32_16x16x32_bf16 v[44:47], v[176:179], v[196:199], v[44:47]
	v_mfma_f32_16x16x32_bf16 v[36:39], v[176:179], v[200:203], v[36:39]
	s_waitcnt lgkmcnt(0)
	ds_read_b128 v[172:175], v67 offset:0
	ds_read_b128 v[176:179], v67 offset:2048
	ds_read_b128 v[188:191], v65 offset:0
	ds_read_b128 v[192:195], v65 offset:2048
	ds_read_b128 v[196:199], v65 offset:4096
	ds_read_b128 v[200:203], v65 offset:6144
	v_mfma_f32_16x16x32_bf16 v[60:63], v[140:143], v[156:159], v[60:63]
	v_mfma_f32_16x16x32_bf16 v[68:71], v[140:143], v[160:163], v[68:71]
	s_add_u32 m0, s4, 0x8000
	s_nop 0
	global_load_lds_dwordx4 v56, s[0:1]
	v_mfma_f32_16x16x32_bf16 v[52:55], v[140:143], v[164:167], v[52:55]
	v_mfma_f32_16x16x32_bf16 v[40:43], v[140:143], v[168:171], v[40:43]
	s_add_u32 m0, s4, 0x9000
	s_nop 0
	global_load_lds_dwordx4 v57, s[0:1]
	v_mfma_f32_16x16x32_bf16 v[72:75], v[144:147], v[156:159], v[72:75]
	v_mfma_f32_16x16x32_bf16 v[48:51], v[144:147], v[160:163], v[48:51]
	s_add_u32 m0, s4, 0xa000
	s_nop 0
	global_load_lds_dwordx4 v58, s[0:1]
	v_mfma_f32_16x16x32_bf16 v[44:47], v[144:147], v[164:167], v[44:47]
	v_mfma_f32_16x16x32_bf16 v[36:39], v[144:147], v[168:171], v[36:39]
	s_add_u32 m0, s4, 0xb000
	s_nop 0
	global_load_lds_dwordx4 v59, s[0:1]
	s_add_u32 m0, s4, 0xc000
	s_nop 0
	global_load_lds_dwordx4 v56, s[2:3]
	s_add_u32 s0, s0, 0x80
	s_addc_u32 s1, s1, 0
	s_add_u32 s2, s2, 0x80
	s_addc_u32 s3, s3, 0
	s_waitcnt vmcnt(0) lgkmcnt(0)
	s_barrier
	ds_read_b128 v[140:143], v66 offset:32768
	ds_read_b128 v[144:147], v66 offset:34816
	ds_read_b128 v[156:159], v64 offset:32768
	ds_read_b128 v[160:163], v64 offset:34816
	ds_read_b128 v[164:167], v64 offset:36864
	ds_read_b128 v[168:171], v64 offset:38912
	v_mfma_f32_16x16x32_bf16 v[60:63], v[172:175], v[188:191], v[60:63]
	v_mfma_f32_16x16x32_bf16 v[68:71], v[172:175], v[192:195], v[68:71]
	v_mfma_f32_16x16x32_bf16 v[52:55], v[172:175], v[196:199], v[52:55]
	v_mfma_f32_16x16x32_bf16 v[40:43], v[172:175], v[200:203], v[40:43]
	v_mfma_f32_16x16x32_bf16 v[72:75], v[176:179], v[188:191], v[72:75]
	v_mfma_f32_16x16x32_bf16 v[48:51], v[176:179], v[192:195], v[48:51]
	v_mfma_f32_16x16x32_bf16 v[44:47], v[176:179], v[196:199], v[44:47]
	v_mfma_f32_16x16x32_bf16 v[36:39], v[176:179], v[200:203], v[36:39]
	s_waitcnt lgkmcnt(0)
	ds_read_b128 v[172:175], v67 offset:32768
	ds_read_b128 v[176:179], v67 offset:34816
	ds_read_b128 v[188:191], v65 offset:32768
	ds_read_b128 v[192:195], v65 offset:34816
	ds_read_b128 v[196:199], v65 offset:36864
	ds_read_b128 v[200:203], v65 offset:38912
	v_mfma_f32_16x16x32_bf16 v[60:63], v[140:143], v[156:159], v[60:63]
	v_mfma_f32_16x16x32_bf16 v[68:71], v[140:143], v[160:163], v[68:71]
	s_add_u32 m0, s4, 0x0
	s_nop 0
	global_load_lds_dwordx4 v56, s[0:1]
	v_mfma_f32_16x16x32_bf16 v[52:55], v[140:143], v[164:167], v[52:55]
	v_mfma_f32_16x16x32_bf16 v[40:43], v[140:143], v[168:171], v[40:43]
	s_add_u32 m0, s4, 0x1000
	s_nop 0
	global_load_lds_dwordx4 v57, s[0:1]
	v_mfma_f32_16x16x32_bf16 v[72:75], v[144:147], v[156:159], v[72:75]
	v_mfma_f32_16x16x32_bf16 v[48:51], v[144:147], v[160:163], v[48:51]
	s_add_u32 m0, s4, 0x2000
	s_nop 0
	global_load_lds_dwordx4 v58, s[0:1]
	v_mfma_f32_16x16x32_bf16 v[44:47], v[144:147], v[164:167], v[44:47]
	v_mfma_f32_16x16x32_bf16 v[36:39], v[144:147], v[168:171], v[36:39]
	s_add_u32 m0, s4, 0x3000
	s_nop 0
	global_load_lds_dwordx4 v59, s[0:1]
	s_add_u32 m0, s4, 0x4000
	s_nop 0
	global_load_lds_dwordx4 v56, s[2:3]
	s_add_u32 s0, s0, 0x80
	s_addc_u32 s1, s1, 0
	s_add_u32 s2, s2, 0x80
	s_addc_u32 s3, s3, 0
	s_waitcnt vmcnt(0) lgkmcnt(0)
	s_barrier
	ds_read_b128 v[140:143], v66 offset:0
	ds_read_b128 v[144:147], v66 offset:2048
	ds_read_b128 v[156:159], v64 offset:0
	ds_read_b128 v[160:163], v64 offset:2048
	ds_read_b128 v[164:167], v64 offset:4096
	ds_read_b128 v[168:171], v64 offset:6144
	v_mfma_f32_16x16x32_bf16 v[60:63], v[172:175], v[188:191], v[60:63]
	v_mfma_f32_16x16x32_bf16 v[68:71], v[172:175], v[192:195], v[68:71]
	v_mfma_f32_16x16x32_bf16 v[52:55], v[172:175], v[196:199], v[52:55]
	v_mfma_f32_16x16x32_bf16 v[40:43], v[172:175], v[200:203], v[40:43]
	v_mfma_f32_16x16x32_bf16 v[72:75], v[176:179], v[188:191], v[72:75]
	v_mfma_f32_16x16x32_bf16 v[48:51], v[176:179], v[192:195], v[48:51]
	v_mfma_f32_16x16x32_bf16 v[44:47], v[176:179], v[196:199], v[44:47]
	v_mfma_f32_16x16x32_bf16 v[36:39], v[176:179], v[200:203], v[36:39]
	s_waitcnt lgkmcnt(0)
	ds_read_b128 v[172:175], v67 offset:0
	ds_read_b128 v[176:179], v67 offset:2048
	ds_read_b128 v[188:191], v65 offset:0
	ds_read_b128 v[192:195], v65 offset:2048
	ds_read_b128 v[196:199], v65 offset:4096
	ds_read_b128 v[200:203], v65 offset:6144
	v_mfma_f32_16x16x32_bf16 v[60:63], v[140:143], v[156:159], v[60:63]
	v_mfma_f32_16x16x32_bf16 v[68:71], v[140:143], v[160:163], v[68:71]
	s_add_u32 m0, s4, 0x8000
	s_nop 0
	global_load_lds_dwordx4 v56, s[0:1]
	v_mfma_f32_16x16x32_bf16 v[52:55], v[140:143], v[164:167], v[52:55]
	v_mfma_f32_16x16x32_bf16 v[40:43], v[140:143], v[168:171], v[40:43]
	s_add_u32 m0, s4, 0x9000
	s_nop 0
	global_load_lds_dwordx4 v57, s[0:1]
	v_mfma_f32_16x16x32_bf16 v[72:75], v[144:147], v[156:159], v[72:75]
	v_mfma_f32_16x16x32_bf16 v[48:51], v[144:147], v[160:163], v[48:51]
	s_add_u32 m0, s4, 0xa000
	s_nop 0
	global_load_lds_dwordx4 v58, s[0:1]
	v_mfma_f32_16x16x32_bf16 v[44:47], v[144:147], v[164:167], v[44:47]
	v_mfma_f32_16x16x32_bf16 v[36:39], v[144:147], v[168:171], v[36:39]
	s_add_u32 m0, s4, 0xb000
	s_nop 0
	global_load_lds_dwordx4 v59, s[0:1]
	s_add_u32 m0, s4, 0xc000
	s_nop 0
	global_load_lds_dwordx4 v56, s[2:3]
	s_add_u32 s0, s0, 0x80
	s_addc_u32 s1, s1, 0
	s_add_u32 s2, s2, 0x80
	s_addc_u32 s3, s3, 0
	s_waitcnt vmcnt(0) lgkmcnt(0)
	s_barrier
	ds_read_b128 v[140:143], v66 offset:32768
	ds_read_b128 v[144:147], v66 offset:34816
	ds_read_b128 v[156:159], v64 offset:32768
	ds_read_b128 v[160:163], v64 offset:34816
	ds_read_b128 v[164:167], v64 offset:36864
	ds_read_b128 v[168:171], v64 offset:38912
	v_mfma_f32_16x16x32_bf16 v[60:63], v[172:175], v[188:191], v[60:63]
	v_mfma_f32_16x16x32_bf16 v[68:71], v[172:175], v[192:195], v[68:71]
	v_mfma_f32_16x16x32_bf16 v[52:55], v[172:175], v[196:199], v[52:55]
	v_mfma_f32_16x16x32_bf16 v[40:43], v[172:175], v[200:203], v[40:43]
	v_mfma_f32_16x16x32_bf16 v[72:75], v[176:179], v[188:191], v[72:75]
	v_mfma_f32_16x16x32_bf16 v[48:51], v[176:179], v[192:195], v[48:51]
	v_mfma_f32_16x16x32_bf16 v[44:47], v[176:179], v[196:199], v[44:47]
	v_mfma_f32_16x16x32_bf16 v[36:39], v[176:179], v[200:203], v[36:39]
	s_waitcnt lgkmcnt(0)
	ds_read_b128 v[172:175], v67 offset:32768
	ds_read_b128 v[176:179], v67 offset:34816
	ds_read_b128 v[188:191], v65 offset:32768
	ds_read_b128 v[192:195], v65 offset:34816
	ds_read_b128 v[196:199], v65 offset:36864
	ds_read_b128 v[200:203], v65 offset:38912
	v_mfma_f32_16x16x32_bf16 v[60:63], v[140:143], v[156:159], v[60:63]
	v_mfma_f32_16x16x32_bf16 v[68:71], v[140:143], v[160:163], v[68:71]
	v_mfma_f32_16x16x32_bf16 v[52:55], v[140:143], v[164:167], v[52:55]
	v_mfma_f32_16x16x32_bf16 v[40:43], v[140:143], v[168:171], v[40:43]
	v_mfma_f32_16x16x32_bf16 v[72:75], v[144:147], v[156:159], v[72:75]
	v_mfma_f32_16x16x32_bf16 v[48:51], v[144:147], v[160:163], v[48:51]
	v_mfma_f32_16x16x32_bf16 v[44:47], v[144:147], v[164:167], v[44:47]
	v_mfma_f32_16x16x32_bf16 v[36:39], v[144:147], v[168:171], v[36:39]
	s_waitcnt vmcnt(0) lgkmcnt(0)
	s_barrier
	v_mfma_f32_16x16x32_bf16 v[60:63], v[172:175], v[188:191], v[60:63]
	v_mfma_f32_16x16x32_bf16 v[68:71], v[172:175], v[192:195], v[68:71]
	v_mfma_f32_16x16x32_bf16 v[52:55], v[172:175], v[196:199], v[52:55]
	v_mfma_f32_16x16x32_bf16 v[40:43], v[172:175], v[200:203], v[40:43]
	v_mfma_f32_16x16x32_bf16 v[72:75], v[176:179], v[188:191], v[72:75]
	v_mfma_f32_16x16x32_bf16 v[48:51], v[176:179], v[192:195], v[48:51]
	v_mfma_f32_16x16x32_bf16 v[44:47], v[176:179], v[196:199], v[44:47]
	v_mfma_f32_16x16x32_bf16 v[36:39], v[176:179], v[200:203], v[36:39]
.Lg1_join:
	s_lshl_b32 s8, s22, 7
	v_cmp_gt_i32_e32 vcc, s19, v94
	s_nop 7
	s_nop 1
	s_and_saveexec_b64 s[0:1], vcc
	s_cbranch_execz .LBB0_423
	s_xor_b64 s[4:5], s[58:59], -1
	s_and_b32 s9, s64, 0x1fffffe
	s_cmp_lt_i32 s9, 12
	s_cbranch_scc1 .LBB0_349
	s_cmp_eq_u32 s9, 12
	s_cselect_b64 s[2:3], -1, 0
	s_cbranch_execz .LBB0_350
	s_branch .LBB0_351
